# stack17 + GEMM epilogue wide stores made write-through (sc1) so the grid barrier's L2 write-back has little left to flush
# baseline (speedup 1.0000x reference)
.LBB0_162:
	v_mul_f32_e32 v151, 0xbfb8aa3b, v124
	v_exp_f32_e32 v151, v151
	v_mul_f32_e32 v152, 0xbfb8aa3b, v125
	v_exp_f32_e32 v153, v152
	v_lshl_or_b32 v152, s54, 7, v146
	v_add_f32_e32 v151, 1.0, v151
	v_rcp_f32_e32 v151, v151
	v_add_f32_e32 v153, 1.0, v153
	v_rcp_f32_e32 v154, v153
	v_lshl_or_b32 v150, s34, 8, v145
	v_mul_f32_e32 v124, v124, v151
	v_mul_f32_e32 v116, v124, v116
	v_mul_f32_e32 v124, v125, v154
	v_mul_f32_e32 v125, 0xbfb8aa3b, v126
	v_exp_f32_e32 v125, v125
	v_mul_f32_e32 v151, 0xbfb8aa3b, v127
	v_exp_f32_e32 v151, v151
	v_mul_f32_e32 v117, v124, v117
	v_add_f32_e32 v124, 1.0, v125
	v_rcp_f32_e32 v124, v124
	v_add_f32_e32 v125, 1.0, v151
	v_rcp_f32_e32 v125, v125
	v_cvt_pk_bf16_f32 v116, v116, v117
	v_mul_f32_e32 v117, v126, v124
	v_mul_f32_e32 v124, 0xbfb8aa3b, v120
	v_exp_f32_e32 v124, v124
	v_mul_f32_e32 v117, v117, v118
	v_mul_f32_e32 v118, v127, v125
	v_mul_f32_e32 v125, 0xbfb8aa3b, v121
	v_exp_f32_e32 v125, v125
	v_mul_f32_e32 v118, v118, v119
	v_add_f32_e32 v119, 1.0, v124
	v_rcp_f32_e32 v119, v119
	v_add_f32_e32 v124, 1.0, v125
	v_rcp_f32_e32 v124, v124
	v_cvt_pk_bf16_f32 v117, v117, v118
	v_mul_f32_e32 v118, v120, v119
	v_mul_f32_e32 v119, 0xbfb8aa3b, v122
	v_exp_f32_e32 v119, v119
	v_mul_f32_e32 v120, 0xbfb8aa3b, v123
	v_exp_f32_e32 v120, v120
	v_mul_f32_e32 v112, v118, v112
	v_mul_f32_e32 v118, v121, v124
	v_mul_f32_e32 v113, v118, v113
	v_add_f32_e32 v118, 1.0, v119
	v_rcp_f32_e32 v119, v118
	v_add_f32_e32 v118, 1.0, v120
	v_rcp_f32_e32 v120, v118
	v_cvt_pk_bf16_f32 v118, v112, v113
	v_mul_f32_e32 v112, v122, v119
	v_mul_f32_e32 v122, 0xbfb8aa3b, v108
	v_mul_f32_e32 v113, v123, v120
	v_mul_f32_e32 v112, v112, v114
	v_mul_f32_e32 v113, v113, v115
	v_exp_f32_e32 v122, v122
	v_mul_f32_e32 v123, 0xbfb8aa3b, v109
	v_ashrrev_i32_e32 v153, 31, v152
	v_cvt_pk_bf16_f32 v119, v112, v113
	v_mov_b64_e32 v[112:113], s[12:13]
	v_exp_f32_e32 v123, v123
	v_mad_i64_i32 v[120:121], s[36:37], v150, s53, v[112:113]
	v_lshlrev_b64 v[114:115], 1, v[152:153]
	v_lshl_add_u64 v[120:121], v[120:121], 0, v[114:115]
	global_store_dwordx4 v[120:121], v[116:119], off sc1
	s_andn2_b64 vcc, exec, s[2:3]
	s_mov_b64 s[2:3], -1
	v_add_f32_e32 v116, 1.0, v122
	v_rcp_f32_e32 v116, v116
	v_add_f32_e32 v117, 1.0, v123
	v_rcp_f32_e32 v117, v117
	v_or_b32_e32 v118, 16, v150
	v_mul_f32_e32 v108, v108, v116
	v_mul_f32_e32 v100, v108, v100
	v_mul_f32_e32 v108, v109, v117
	v_mul_f32_e32 v109, 0xbfb8aa3b, v110
	v_exp_f32_e32 v109, v109
	v_mul_f32_e32 v116, 0xbfb8aa3b, v111
	v_exp_f32_e32 v116, v116
	v_mul_f32_e32 v101, v108, v101
	v_add_f32_e32 v108, 1.0, v109
	v_rcp_f32_e32 v108, v108
	v_add_f32_e32 v109, 1.0, v116
	v_rcp_f32_e32 v109, v109
	v_cvt_pk_bf16_f32 v100, v100, v101
	v_mul_f32_e32 v101, v110, v108
	v_mul_f32_e32 v108, 0xbfb8aa3b, v104
	v_exp_f32_e32 v108, v108
	v_mul_f32_e32 v101, v101, v102
	v_mul_f32_e32 v102, v111, v109
	v_mul_f32_e32 v109, 0xbfb8aa3b, v105
	v_exp_f32_e32 v109, v109
	v_mul_f32_e32 v102, v102, v103
	v_add_f32_e32 v103, 1.0, v108
	v_rcp_f32_e32 v103, v103
	v_add_f32_e32 v108, 1.0, v109
	v_rcp_f32_e32 v108, v108
	v_cvt_pk_bf16_f32 v101, v101, v102
	v_mul_f32_e32 v102, v104, v103
	v_mul_f32_e32 v103, 0xbfb8aa3b, v106
	v_exp_f32_e32 v103, v103
	v_mul_f32_e32 v104, 0xbfb8aa3b, v107
	v_exp_f32_e32 v104, v104
	v_mul_f32_e32 v96, v102, v96
	v_mul_f32_e32 v102, v105, v108
	v_mul_f32_e32 v97, v102, v97
	v_add_f32_e32 v102, 1.0, v103
	v_rcp_f32_e32 v103, v102
	v_add_f32_e32 v102, 1.0, v104
	v_rcp_f32_e32 v104, v102
	v_cvt_pk_bf16_f32 v102, v96, v97
	v_mul_f32_e32 v96, v106, v103
	v_mul_f32_e32 v96, v96, v98
	v_mul_f32_e32 v97, v107, v104
	v_mul_f32_e32 v98, 0xbfb8aa3b, v92
	v_mul_f32_e32 v97, v97, v99
	v_exp_f32_e32 v98, v98
	v_mul_f32_e32 v99, 0xbfb8aa3b, v93
	v_exp_f32_e32 v99, v99
	v_cvt_pk_bf16_f32 v103, v96, v97
	v_mad_i64_i32 v[96:97], s[36:37], v118, s53, v[112:113]
	v_lshl_add_u64 v[96:97], v[96:97], 0, v[114:115]
	global_store_dwordx4 v[96:97], v[100:103], off sc1
	v_add_f32_e32 v96, 1.0, v98
	v_rcp_f32_e32 v96, v96
	v_add_f32_e32 v97, 1.0, v99
	v_rcp_f32_e32 v97, v97
	v_or_b32_e32 v98, 32, v150
	v_mul_f32_e32 v92, v92, v96
	v_mul_f32_e32 v84, v92, v84
	v_mul_f32_e32 v92, v93, v97
	v_mul_f32_e32 v93, 0xbfb8aa3b, v94
	v_exp_f32_e32 v93, v93
	v_mul_f32_e32 v96, 0xbfb8aa3b, v95
	v_exp_f32_e32 v96, v96
	v_mul_f32_e32 v85, v92, v85
	v_add_f32_e32 v92, 1.0, v93
	v_rcp_f32_e32 v92, v92
	v_add_f32_e32 v93, 1.0, v96
	v_rcp_f32_e32 v93, v93
	v_cvt_pk_bf16_f32 v84, v84, v85
	v_mul_f32_e32 v85, v94, v92
	v_mul_f32_e32 v92, 0xbfb8aa3b, v88
	v_exp_f32_e32 v92, v92
	v_mul_f32_e32 v85, v85, v86
	v_mul_f32_e32 v86, v95, v93
	v_mul_f32_e32 v93, 0xbfb8aa3b, v89
	v_exp_f32_e32 v93, v93
	v_mul_f32_e32 v86, v86, v87
	v_add_f32_e32 v87, 1.0, v92
	v_rcp_f32_e32 v87, v87
	v_add_f32_e32 v92, 1.0, v93
	v_rcp_f32_e32 v92, v92
	v_cvt_pk_bf16_f32 v85, v85, v86
	v_mul_f32_e32 v86, v88, v87
	v_mul_f32_e32 v87, 0xbfb8aa3b, v90
	v_exp_f32_e32 v87, v87
	v_mul_f32_e32 v88, 0xbfb8aa3b, v91
	v_exp_f32_e32 v88, v88
	v_mul_f32_e32 v80, v86, v80
	v_mul_f32_e32 v86, v89, v92
	v_mul_f32_e32 v81, v86, v81
	v_add_f32_e32 v86, 1.0, v87
	v_rcp_f32_e32 v87, v86
	v_add_f32_e32 v86, 1.0, v88
	v_rcp_f32_e32 v88, v86
	v_cvt_pk_bf16_f32 v86, v80, v81
	v_mul_f32_e32 v80, v90, v87
	v_mul_f32_e32 v80, v80, v82
	v_mul_f32_e32 v81, v91, v88
	v_mul_f32_e32 v82, 0xbfb8aa3b, v76
	v_mul_f32_e32 v81, v81, v83
	v_exp_f32_e32 v82, v82
	v_mul_f32_e32 v83, 0xbfb8aa3b, v77
	v_exp_f32_e32 v83, v83
	v_cvt_pk_bf16_f32 v87, v80, v81
	v_mad_i64_i32 v[80:81], s[36:37], v98, s53, v[112:113]
	v_lshl_add_u64 v[80:81], v[80:81], 0, v[114:115]
	global_store_dwordx4 v[80:81], v[84:87], off sc1
	v_add_f32_e32 v80, 1.0, v82
	v_rcp_f32_e32 v80, v80
	v_add_f32_e32 v81, 1.0, v83
	v_rcp_f32_e32 v81, v81
	v_or_b32_e32 v82, 48, v150
	v_mul_f32_e32 v76, v76, v80
	v_mul_f32_e32 v68, v76, v68
	v_mul_f32_e32 v76, v77, v81
	v_mul_f32_e32 v77, 0xbfb8aa3b, v78
	v_exp_f32_e32 v77, v77
	v_mul_f32_e32 v80, 0xbfb8aa3b, v79
	v_exp_f32_e32 v80, v80
	v_mul_f32_e32 v69, v76, v69
	v_add_f32_e32 v76, 1.0, v77
	v_rcp_f32_e32 v76, v76
	v_add_f32_e32 v77, 1.0, v80
	v_rcp_f32_e32 v77, v77
	v_cvt_pk_bf16_f32 v68, v68, v69
	v_mul_f32_e32 v69, v78, v76
	v_mul_f32_e32 v76, 0xbfb8aa3b, v72
	v_exp_f32_e32 v76, v76
	v_mul_f32_e32 v69, v69, v70
	v_mul_f32_e32 v70, v79, v77
	v_mul_f32_e32 v77, 0xbfb8aa3b, v73
	v_exp_f32_e32 v77, v77
	v_mul_f32_e32 v70, v70, v71
	v_add_f32_e32 v71, 1.0, v76
	v_rcp_f32_e32 v71, v71
	v_add_f32_e32 v76, 1.0, v77
	v_rcp_f32_e32 v76, v76
	v_cvt_pk_bf16_f32 v69, v69, v70
	v_mul_f32_e32 v70, v72, v71
	v_mul_f32_e32 v71, 0xbfb8aa3b, v74
	v_exp_f32_e32 v71, v71
	v_mul_f32_e32 v72, 0xbfb8aa3b, v75
	v_exp_f32_e32 v72, v72
	v_mul_f32_e32 v64, v70, v64
	v_mul_f32_e32 v70, v73, v76
	v_mul_f32_e32 v65, v70, v65
	v_add_f32_e32 v70, 1.0, v71
	v_rcp_f32_e32 v71, v70
	v_add_f32_e32 v70, 1.0, v72
	v_rcp_f32_e32 v72, v70
	v_cvt_pk_bf16_f32 v70, v64, v65
	v_mul_f32_e32 v64, v74, v71
	v_mul_f32_e32 v64, v64, v66
	v_mul_f32_e32 v65, v75, v72
	v_mul_f32_e32 v66, 0xbfb8aa3b, v60
	v_mul_f32_e32 v65, v65, v67
	v_exp_f32_e32 v66, v66
	v_mul_f32_e32 v67, 0xbfb8aa3b, v61
	v_exp_f32_e32 v67, v67
	v_cvt_pk_bf16_f32 v71, v64, v65
	v_mad_i64_i32 v[64:65], s[36:37], v82, s53, v[112:113]
	v_lshl_add_u64 v[64:65], v[64:65], 0, v[114:115]
	global_store_dwordx4 v[64:65], v[68:71], off sc1
	v_add_f32_e32 v64, 1.0, v66
	v_rcp_f32_e32 v64, v64
	v_add_f32_e32 v65, 1.0, v67
	v_rcp_f32_e32 v65, v65
	v_or_b32_e32 v66, 0x80, v150
	v_mul_f32_e32 v60, v60, v64
	v_mul_f32_e32 v52, v60, v52
	v_mul_f32_e32 v60, v61, v65
	v_mul_f32_e32 v61, 0xbfb8aa3b, v62
	v_exp_f32_e32 v61, v61
	v_mul_f32_e32 v64, 0xbfb8aa3b, v63
	v_exp_f32_e32 v64, v64
	v_mul_f32_e32 v53, v60, v53
	v_add_f32_e32 v60, 1.0, v61
	v_rcp_f32_e32 v60, v60
	v_add_f32_e32 v61, 1.0, v64
	v_rcp_f32_e32 v61, v61
	v_cvt_pk_bf16_f32 v52, v52, v53
	v_mul_f32_e32 v53, v62, v60
	v_mul_f32_e32 v60, 0xbfb8aa3b, v56
	v_exp_f32_e32 v60, v60
	v_mul_f32_e32 v53, v53, v54
	v_mul_f32_e32 v54, v63, v61
	v_mul_f32_e32 v61, 0xbfb8aa3b, v57
	v_exp_f32_e32 v61, v61
	v_mul_f32_e32 v54, v54, v55
	v_add_f32_e32 v55, 1.0, v60
	v_rcp_f32_e32 v55, v55
	v_add_f32_e32 v60, 1.0, v61
	v_rcp_f32_e32 v60, v60
	v_cvt_pk_bf16_f32 v53, v53, v54
	v_mul_f32_e32 v54, v56, v55
	v_mul_f32_e32 v55, 0xbfb8aa3b, v58
	v_exp_f32_e32 v55, v55
	v_mul_f32_e32 v56, 0xbfb8aa3b, v59
	v_exp_f32_e32 v56, v56
	v_mul_f32_e32 v48, v54, v48
	v_mul_f32_e32 v54, v57, v60
	v_mul_f32_e32 v49, v54, v49
	v_add_f32_e32 v54, 1.0, v55
	v_rcp_f32_e32 v55, v54
	v_add_f32_e32 v54, 1.0, v56
	v_rcp_f32_e32 v56, v54
	v_cvt_pk_bf16_f32 v54, v48, v49
	v_mul_f32_e32 v48, v58, v55
	v_mul_f32_e32 v48, v48, v50
	v_mul_f32_e32 v49, v59, v56
	v_mul_f32_e32 v50, 0xbfb8aa3b, v44
	v_mul_f32_e32 v49, v49, v51
	v_exp_f32_e32 v50, v50
	v_mul_f32_e32 v51, 0xbfb8aa3b, v45
	v_exp_f32_e32 v51, v51
	v_cvt_pk_bf16_f32 v55, v48, v49
	v_mad_i64_i32 v[48:49], s[36:37], v66, s53, v[112:113]
	v_lshl_add_u64 v[48:49], v[48:49], 0, v[114:115]
	global_store_dwordx4 v[48:49], v[52:55], off sc1
	v_add_f32_e32 v48, 1.0, v50
	v_rcp_f32_e32 v48, v48
	v_add_f32_e32 v49, 1.0, v51
	v_rcp_f32_e32 v49, v49
	v_or_b32_e32 v50, 0x90, v150
	v_mul_f32_e32 v44, v44, v48
	v_mul_f32_e32 v36, v44, v36
	v_mul_f32_e32 v44, v45, v49
	v_mul_f32_e32 v45, 0xbfb8aa3b, v46
	v_exp_f32_e32 v45, v45
	v_mul_f32_e32 v48, 0xbfb8aa3b, v47
	v_exp_f32_e32 v48, v48
	v_mul_f32_e32 v37, v44, v37
	v_add_f32_e32 v44, 1.0, v45
	v_rcp_f32_e32 v44, v44
	v_add_f32_e32 v45, 1.0, v48
	v_rcp_f32_e32 v45, v45
	v_cvt_pk_bf16_f32 v36, v36, v37
	v_mul_f32_e32 v37, v46, v44
	v_mul_f32_e32 v44, 0xbfb8aa3b, v40
	v_exp_f32_e32 v44, v44
	v_mul_f32_e32 v37, v37, v38
	v_mul_f32_e32 v38, v47, v45
	v_mul_f32_e32 v45, 0xbfb8aa3b, v41
	v_exp_f32_e32 v45, v45
	v_mul_f32_e32 v38, v38, v39
	v_add_f32_e32 v39, 1.0, v44
	v_rcp_f32_e32 v39, v39
	v_add_f32_e32 v44, 1.0, v45
	v_rcp_f32_e32 v44, v44
	v_cvt_pk_bf16_f32 v37, v37, v38
	v_mul_f32_e32 v38, v40, v39
	v_mul_f32_e32 v39, 0xbfb8aa3b, v42
	v_exp_f32_e32 v39, v39
	v_mul_f32_e32 v40, 0xbfb8aa3b, v43
	v_exp_f32_e32 v40, v40
	v_mul_f32_e32 v32, v38, v32
	v_mul_f32_e32 v38, v41, v44
	v_mul_f32_e32 v33, v38, v33
	v_add_f32_e32 v38, 1.0, v39
	v_rcp_f32_e32 v39, v38
	v_add_f32_e32 v38, 1.0, v40
	v_rcp_f32_e32 v40, v38
	v_cvt_pk_bf16_f32 v38, v32, v33
	v_mul_f32_e32 v32, v42, v39
	v_mul_f32_e32 v32, v32, v34
	v_mul_f32_e32 v33, v43, v40
	v_mul_f32_e32 v34, 0xbfb8aa3b, v28
	v_mul_f32_e32 v33, v33, v35
	v_exp_f32_e32 v34, v34
	v_mul_f32_e32 v35, 0xbfb8aa3b, v29
	v_exp_f32_e32 v35, v35
	v_cvt_pk_bf16_f32 v39, v32, v33
	v_mad_i64_i32 v[32:33], s[36:37], v50, s53, v[112:113]
	v_lshl_add_u64 v[32:33], v[32:33], 0, v[114:115]
	global_store_dwordx4 v[32:33], v[36:39], off sc1
	v_add_f32_e32 v32, 1.0, v34
	v_rcp_f32_e32 v32, v32
	v_add_f32_e32 v33, 1.0, v35
	v_rcp_f32_e32 v33, v33
	v_or_b32_e32 v34, 0xa0, v150
	v_mul_f32_e32 v28, v28, v32
	v_mul_f32_e32 v20, v28, v20
	v_mul_f32_e32 v28, v29, v33
	v_mul_f32_e32 v29, 0xbfb8aa3b, v30
	v_exp_f32_e32 v29, v29
	v_mul_f32_e32 v32, 0xbfb8aa3b, v31
	v_exp_f32_e32 v32, v32
	v_mul_f32_e32 v21, v28, v21
	v_add_f32_e32 v28, 1.0, v29
	v_rcp_f32_e32 v28, v28
	v_add_f32_e32 v29, 1.0, v32
	v_rcp_f32_e32 v29, v29
	v_cvt_pk_bf16_f32 v20, v20, v21
	v_mul_f32_e32 v21, v30, v28
	v_mul_f32_e32 v28, 0xbfb8aa3b, v24
	v_exp_f32_e32 v28, v28
	v_mul_f32_e32 v21, v21, v22
	v_mul_f32_e32 v22, v31, v29
	v_mul_f32_e32 v29, 0xbfb8aa3b, v25
	v_exp_f32_e32 v29, v29
	v_mul_f32_e32 v22, v22, v23
	v_add_f32_e32 v23, 1.0, v28
	v_rcp_f32_e32 v23, v23
	v_add_f32_e32 v28, 1.0, v29
	v_rcp_f32_e32 v28, v28
	v_cvt_pk_bf16_f32 v21, v21, v22
	v_mul_f32_e32 v22, v24, v23
	v_mul_f32_e32 v23, 0xbfb8aa3b, v26
	v_exp_f32_e32 v23, v23
	v_mul_f32_e32 v24, 0xbfb8aa3b, v27
	v_exp_f32_e32 v24, v24
	v_mul_f32_e32 v16, v22, v16
	v_mul_f32_e32 v22, v25, v28
	v_mul_f32_e32 v17, v22, v17
	v_add_f32_e32 v22, 1.0, v23
	v_rcp_f32_e32 v23, v22
	v_add_f32_e32 v22, 1.0, v24
	v_rcp_f32_e32 v24, v22
	v_cvt_pk_bf16_f32 v22, v16, v17
	v_mul_f32_e32 v16, v26, v23
	v_mul_f32_e32 v16, v16, v18
	v_mul_f32_e32 v17, v27, v24
	v_mul_f32_e32 v18, 0xbfb8aa3b, v12
	v_mul_f32_e32 v17, v17, v19
	v_exp_f32_e32 v18, v18
	v_mul_f32_e32 v19, 0xbfb8aa3b, v13
	v_exp_f32_e32 v19, v19
	v_cvt_pk_bf16_f32 v23, v16, v17
	v_mad_i64_i32 v[16:17], s[36:37], v34, s53, v[112:113]
	v_lshl_add_u64 v[16:17], v[16:17], 0, v[114:115]
	global_store_dwordx4 v[16:17], v[20:23], off sc1
	v_add_f32_e32 v16, 1.0, v18
	v_rcp_f32_e32 v16, v16
	v_add_f32_e32 v17, 1.0, v19
	v_rcp_f32_e32 v17, v17
	v_or_b32_e32 v18, 0xb0, v150
	v_mul_f32_e32 v12, v12, v16
	v_mul_f32_e32 v4, v12, v4
	v_mul_f32_e32 v12, v13, v17
	v_mul_f32_e32 v13, 0xbfb8aa3b, v14
	v_exp_f32_e32 v13, v13
	v_mul_f32_e32 v16, 0xbfb8aa3b, v15
	v_exp_f32_e32 v16, v16
	v_mul_f32_e32 v5, v12, v5
	v_add_f32_e32 v12, 1.0, v13
	v_rcp_f32_e32 v12, v12
	v_add_f32_e32 v13, 1.0, v16
	v_rcp_f32_e32 v13, v13
	v_cvt_pk_bf16_f32 v4, v4, v5
	v_mul_f32_e32 v5, v14, v12
	v_mul_f32_e32 v12, 0xbfb8aa3b, v8
	v_exp_f32_e32 v12, v12
	v_mul_f32_e32 v5, v5, v6
	v_mul_f32_e32 v6, v15, v13
	v_mul_f32_e32 v13, 0xbfb8aa3b, v9
	v_exp_f32_e32 v13, v13
	v_mul_f32_e32 v6, v6, v7
	v_add_f32_e32 v7, 1.0, v12
	v_rcp_f32_e32 v7, v7
	v_add_f32_e32 v12, 1.0, v13
	v_rcp_f32_e32 v12, v12
	v_cvt_pk_bf16_f32 v5, v5, v6
	v_mul_f32_e32 v6, v8, v7
	v_mul_f32_e32 v7, 0xbfb8aa3b, v10
	v_exp_f32_e32 v7, v7
	v_mul_f32_e32 v8, 0xbfb8aa3b, v11
	v_exp_f32_e32 v8, v8
	v_mul_f32_e32 v0, v6, v0
	v_mul_f32_e32 v6, v9, v12
	v_mul_f32_e32 v1, v6, v1
	v_add_f32_e32 v6, 1.0, v7
	v_rcp_f32_e32 v7, v6
	v_add_f32_e32 v6, 1.0, v8
	v_rcp_f32_e32 v8, v6
	v_cvt_pk_bf16_f32 v6, v0, v1
	v_mul_f32_e32 v0, v10, v7
	v_mul_f32_e32 v0, v0, v2
	v_mul_f32_e32 v1, v11, v8
	v_mul_f32_e32 v1, v1, v3
	v_cvt_pk_bf16_f32 v7, v0, v1
	v_mad_i64_i32 v[0:1], s[36:37], v18, s53, v[112:113]
	v_lshl_add_u64 v[0:1], v[0:1], 0, v[114:115]
	global_store_dwordx4 v[0:1], v[4:7], off sc1
	s_cbranch_vccnz .LBB0_155
	s_andn2_b64 vcc, exec, s[8:9]
	s_cbranch_vccnz .LBB0_154
	s_barrier
	s_branch .LBB0_154

.LBB0_251:
	v_lshl_or_b32 v144, s11, 8, v159
	v_lshl_or_b32 v146, s62, 8, v160
	v_ashrrev_i32_e32 v145, 31, v144
	v_ashrrev_i32_e32 v147, 31, v146
	v_lshlrev_b64 v[150:151], 11, v[144:145]
	v_lshl_add_u64 v[154:155], v[150:151], 0, v[146:147]
	v_lshl_add_u64 v[148:149], v[154:155], 2, s[18:19]
	global_load_dwordx4 v[164:167], v[148:149], off
	global_load_dwordx4 v[168:171], v[148:149], off offset:16
	v_cndmask_b32_e64 v152, 0, 1, s[38:39]
	v_cmp_ne_u32_e64 s[6:7], 1, v152
	s_andn2_b64 vcc, exec, s[38:39]
	v_lshl_add_u64 v[152:153], v[154:155], 2, s[12:13]
	s_waitcnt vmcnt(0)
	v_pk_fma_f32 v[126:127], v[126:127], 0.5, v[166:167] op_sel_hi:[1,0,1]
	v_pk_fma_f32 v[124:125], v[124:125], 0.5, v[164:165] op_sel_hi:[1,0,1]
	v_pk_fma_f32 v[122:123], v[122:123], 0.5, v[170:171] op_sel_hi:[1,0,1]
	v_pk_fma_f32 v[120:121], v[120:121], 0.5, v[168:169] op_sel_hi:[1,0,1]
	s_cbranch_vccnz .LBB0_253
	global_store_dwordx4 v[152:153], v[124:127], off sc1
	global_store_dwordx4 v[152:153], v[120:123], off offset:16 sc1
.LBB0_253:
	v_lshl_add_u64 v[154:155], v[154:155], 1, s[34:35]
	v_cvt_pk_bf16_f32 v164, v124, v125
	v_cvt_pk_bf16_f32 v165, v126, v127
	v_cvt_pk_bf16_f32 v166, v120, v121
	v_cvt_pk_bf16_f32 v167, v122, v123
	global_store_dwordx4 v[154:155], v[164:167], off sc1
	global_load_dwordx4 v[164:167], v[148:149], off offset:512
	s_nop 0
	global_load_dwordx4 v[168:171], v[148:149], off offset:528
	s_and_b64 vcc, exec, s[6:7]
	s_waitcnt vmcnt(1)
	v_pk_fma_f32 v[118:119], v[118:119], 0.5, v[166:167] op_sel_hi:[1,0,1]
	v_pk_fma_f32 v[116:117], v[116:117], 0.5, v[164:165] op_sel_hi:[1,0,1]
	s_waitcnt vmcnt(0)
	v_pk_fma_f32 v[114:115], v[114:115], 0.5, v[170:171] op_sel_hi:[1,0,1]
	v_pk_fma_f32 v[112:113], v[112:113], 0.5, v[168:169] op_sel_hi:[1,0,1]
	s_cbranch_vccnz .LBB0_255
	global_store_dwordx4 v[152:153], v[116:119], off offset:512 sc1
	global_store_dwordx4 v[152:153], v[112:115], off offset:528 sc1
.LBB0_255:
	v_or_b32_e32 v148, 0x80, v146
	v_mov_b32_e32 v149, v147
	v_lshl_add_u64 v[154:155], v[150:151], 0, v[148:149]
	v_cndmask_b32_e64 v164, 0, 1, s[40:41]
	v_lshl_add_u64 v[154:155], v[154:155], 1, s[34:35]
	v_cmp_ne_u32_e64 s[8:9], 1, v164
	s_andn2_b64 vcc, exec, s[40:41]
	v_cvt_pk_bf16_f32 v150, v116, v117
	v_cvt_pk_bf16_f32 v151, v118, v119
	v_cvt_pk_bf16_f32 v152, v112, v113
	v_cvt_pk_bf16_f32 v153, v114, v115
	global_store_dwordx4 v[154:155], v[150:153], off sc1
	s_cbranch_vccnz .LBB0_259
	v_mul_f32_e32 v125, v125, v125
	v_mul_f32_e32 v121, v121, v121
	v_mul_f32_e32 v117, v117, v117
	v_mul_f32_e32 v113, v113, v113
	v_fmac_f32_e32 v125, v124, v124
	v_mul_f32_e32 v124, v127, v127
	v_fmac_f32_e32 v121, v120, v120
	v_mul_f32_e32 v120, v123, v123
	v_fmac_f32_e32 v117, v116, v116
	v_mul_f32_e32 v116, v119, v119
	v_fmac_f32_e32 v113, v112, v112
	v_mul_f32_e32 v112, v115, v115
	v_fmac_f32_e32 v124, v126, v126
	v_fmac_f32_e32 v120, v122, v122
	v_fmac_f32_e32 v116, v118, v118
	v_fmac_f32_e32 v112, v114, v114
	v_add_f32_e32 v124, v125, v124
	v_add_f32_e32 v120, v121, v120
	v_add_f32_e32 v116, v117, v116
	v_add_f32_e32 v112, v113, v112
	v_add_f32_e32 v120, v124, v120
	v_add_f32_e32 v112, v116, v112
	v_add_f32_e32 v112, v120, v112
	ds_bpermute_b32 v113, v157, v112
	s_waitcnt lgkmcnt(0)
	v_add_f32_e32 v112, v112, v113
	ds_bpermute_b32 v113, v158, v112
	s_and_saveexec_b64 s[46:47], s[2:3]
	s_cbranch_execz .LBB0_258
	v_lshl_add_u64 v[114:115], v[144:145], 2, s[14:15]
	s_waitcnt lgkmcnt(0)
	v_add_f32_e32 v112, v112, v113
	global_atomic_add_f32 v[114:115], v112, off

.LBB0_259:
	v_or_b32_e32 v112, 16, v144
	s_waitcnt lgkmcnt(0)
	v_ashrrev_i32_e32 v113, 31, v112
	v_lshlrev_b64 v[112:113], 11, v[112:113]
	v_lshl_add_u64 v[118:119], v[112:113], 0, v[146:147]
	v_lshl_add_u64 v[116:117], v[118:119], 2, s[18:19]
	global_load_dwordx4 v[120:123], v[116:117], off
	global_load_dwordx4 v[124:127], v[116:117], off offset:16
	s_and_b64 vcc, exec, s[6:7]
	v_lshl_add_u64 v[114:115], v[118:119], 2, s[12:13]
	s_waitcnt vmcnt(1)
	v_pk_fma_f32 v[110:111], v[110:111], 0.5, v[122:123] op_sel_hi:[1,0,1]
	v_pk_fma_f32 v[108:109], v[108:109], 0.5, v[120:121] op_sel_hi:[1,0,1]
	s_waitcnt vmcnt(0)
	v_pk_fma_f32 v[106:107], v[106:107], 0.5, v[126:127] op_sel_hi:[1,0,1]
	v_pk_fma_f32 v[104:105], v[104:105], 0.5, v[124:125] op_sel_hi:[1,0,1]
	s_cbranch_vccnz .LBB0_261
	global_store_dwordx4 v[114:115], v[108:111], off sc1
	global_store_dwordx4 v[114:115], v[104:107], off offset:16 sc1
.LBB0_261:
	v_lshl_add_u64 v[118:119], v[118:119], 1, s[34:35]
	v_cvt_pk_bf16_f32 v120, v108, v109
	v_cvt_pk_bf16_f32 v121, v110, v111
	v_cvt_pk_bf16_f32 v122, v104, v105
	v_cvt_pk_bf16_f32 v123, v106, v107
	global_store_dwordx4 v[118:119], v[120:123], off sc1
	global_load_dwordx4 v[118:121], v[116:117], off offset:512
	s_nop 0
	global_load_dwordx4 v[122:125], v[116:117], off offset:528
	s_and_b64 vcc, exec, s[6:7]
	s_waitcnt vmcnt(1)
	v_pk_fma_f32 v[102:103], v[102:103], 0.5, v[120:121] op_sel_hi:[1,0,1]
	v_pk_fma_f32 v[100:101], v[100:101], 0.5, v[118:119] op_sel_hi:[1,0,1]
	s_waitcnt vmcnt(0)
	v_pk_fma_f32 v[98:99], v[98:99], 0.5, v[124:125] op_sel_hi:[1,0,1]
	v_pk_fma_f32 v[96:97], v[96:97], 0.5, v[122:123] op_sel_hi:[1,0,1]
	s_cbranch_vccnz .LBB0_263
	global_store_dwordx4 v[114:115], v[100:103], off offset:512 sc1
	global_store_dwordx4 v[114:115], v[96:99], off offset:528 sc1
.LBB0_263:
	v_lshl_add_u64 v[116:117], v[112:113], 0, v[148:149]
	v_lshl_add_u64 v[116:117], v[116:117], 1, s[34:35]
	s_and_b64 vcc, exec, s[8:9]
	v_cvt_pk_bf16_f32 v112, v100, v101
	v_cvt_pk_bf16_f32 v113, v102, v103
	v_cvt_pk_bf16_f32 v114, v96, v97
	v_cvt_pk_bf16_f32 v115, v98, v99
	global_store_dwordx4 v[116:117], v[112:115], off sc1
	s_cbranch_vccnz .LBB0_267
	v_mul_f32_e32 v109, v109, v109
	v_mul_f32_e32 v105, v105, v105
	v_mul_f32_e32 v101, v101, v101
	v_mul_f32_e32 v97, v97, v97
	v_fmac_f32_e32 v109, v108, v108
	v_mul_f32_e32 v108, v111, v111
	v_fmac_f32_e32 v105, v104, v104
	v_mul_f32_e32 v104, v107, v107
	v_fmac_f32_e32 v101, v100, v100
	v_mul_f32_e32 v100, v103, v103
	v_fmac_f32_e32 v97, v96, v96
	v_mul_f32_e32 v96, v99, v99
	v_fmac_f32_e32 v108, v110, v110
	v_fmac_f32_e32 v104, v106, v106
	v_fmac_f32_e32 v100, v102, v102
	v_fmac_f32_e32 v96, v98, v98
	v_add_f32_e32 v108, v109, v108
	v_add_f32_e32 v104, v105, v104
	v_add_f32_e32 v100, v101, v100
	v_add_f32_e32 v96, v97, v96
	v_add_f32_e32 v104, v108, v104
	v_add_f32_e32 v96, v100, v96
	v_add_f32_e32 v96, v104, v96
	ds_bpermute_b32 v97, v157, v96
	s_waitcnt lgkmcnt(0)
	v_add_f32_e32 v96, v96, v97
	ds_bpermute_b32 v97, v158, v96
	s_and_saveexec_b64 s[46:47], s[2:3]
	s_cbranch_execz .LBB0_266
	v_lshl_add_u64 v[98:99], v[144:145], 2, s[14:15]
	s_waitcnt lgkmcnt(0)
	v_add_f32_e32 v96, v96, v97
	global_atomic_add_f32 v[98:99], v96, off offset:64

.LBB0_267:
	v_or_b32_e32 v96, 32, v144
	s_waitcnt lgkmcnt(0)
	v_ashrrev_i32_e32 v97, 31, v96
	v_lshlrev_b64 v[96:97], 11, v[96:97]
	v_lshl_add_u64 v[102:103], v[96:97], 0, v[146:147]
	v_lshl_add_u64 v[100:101], v[102:103], 2, s[18:19]
	global_load_dwordx4 v[104:107], v[100:101], off
	global_load_dwordx4 v[108:111], v[100:101], off offset:16
	s_and_b64 vcc, exec, s[6:7]
	v_lshl_add_u64 v[98:99], v[102:103], 2, s[12:13]
	s_waitcnt vmcnt(1)
	v_pk_fma_f32 v[94:95], v[94:95], 0.5, v[106:107] op_sel_hi:[1,0,1]
	v_pk_fma_f32 v[92:93], v[92:93], 0.5, v[104:105] op_sel_hi:[1,0,1]
	s_waitcnt vmcnt(0)
	v_pk_fma_f32 v[90:91], v[90:91], 0.5, v[110:111] op_sel_hi:[1,0,1]
	v_pk_fma_f32 v[88:89], v[88:89], 0.5, v[108:109] op_sel_hi:[1,0,1]
	s_cbranch_vccnz .LBB0_269
	global_store_dwordx4 v[98:99], v[92:95], off sc1
	global_store_dwordx4 v[98:99], v[88:91], off offset:16 sc1
.LBB0_269:
	v_lshl_add_u64 v[102:103], v[102:103], 1, s[34:35]
	v_cvt_pk_bf16_f32 v104, v92, v93
	v_cvt_pk_bf16_f32 v105, v94, v95
	v_cvt_pk_bf16_f32 v106, v88, v89
	v_cvt_pk_bf16_f32 v107, v90, v91
	global_store_dwordx4 v[102:103], v[104:107], off sc1
	global_load_dwordx4 v[102:105], v[100:101], off offset:512
	s_nop 0
	global_load_dwordx4 v[106:109], v[100:101], off offset:528
	s_and_b64 vcc, exec, s[6:7]
	s_waitcnt vmcnt(1)
	v_pk_fma_f32 v[86:87], v[86:87], 0.5, v[104:105] op_sel_hi:[1,0,1]
	v_pk_fma_f32 v[84:85], v[84:85], 0.5, v[102:103] op_sel_hi:[1,0,1]
	s_waitcnt vmcnt(0)
	v_pk_fma_f32 v[82:83], v[82:83], 0.5, v[108:109] op_sel_hi:[1,0,1]
	v_pk_fma_f32 v[80:81], v[80:81], 0.5, v[106:107] op_sel_hi:[1,0,1]
	s_cbranch_vccnz .LBB0_271
	global_store_dwordx4 v[98:99], v[84:87], off offset:512 sc1
	global_store_dwordx4 v[98:99], v[80:83], off offset:528 sc1
.LBB0_271:
	v_lshl_add_u64 v[100:101], v[96:97], 0, v[148:149]
	v_lshl_add_u64 v[100:101], v[100:101], 1, s[34:35]
	s_and_b64 vcc, exec, s[8:9]
	v_cvt_pk_bf16_f32 v96, v84, v85
	v_cvt_pk_bf16_f32 v97, v86, v87
	v_cvt_pk_bf16_f32 v98, v80, v81
	v_cvt_pk_bf16_f32 v99, v82, v83
	global_store_dwordx4 v[100:101], v[96:99], off sc1
	s_cbranch_vccnz .LBB0_275
	v_mul_f32_e32 v93, v93, v93
	v_mul_f32_e32 v89, v89, v89
	v_mul_f32_e32 v85, v85, v85
	v_mul_f32_e32 v81, v81, v81
	v_fmac_f32_e32 v93, v92, v92
	v_mul_f32_e32 v92, v95, v95
	v_fmac_f32_e32 v89, v88, v88
	v_mul_f32_e32 v88, v91, v91
	v_fmac_f32_e32 v85, v84, v84
	v_mul_f32_e32 v84, v87, v87
	v_fmac_f32_e32 v81, v80, v80
	v_mul_f32_e32 v80, v83, v83
	v_fmac_f32_e32 v92, v94, v94
	v_fmac_f32_e32 v88, v90, v90
	v_fmac_f32_e32 v84, v86, v86
	v_fmac_f32_e32 v80, v82, v82
	v_add_f32_e32 v92, v93, v92
	v_add_f32_e32 v88, v89, v88
	v_add_f32_e32 v84, v85, v84
	v_add_f32_e32 v80, v81, v80
	v_add_f32_e32 v88, v92, v88
	v_add_f32_e32 v80, v84, v80
	v_add_f32_e32 v80, v88, v80
	ds_bpermute_b32 v81, v157, v80
	s_waitcnt lgkmcnt(0)
	v_add_f32_e32 v80, v80, v81
	ds_bpermute_b32 v81, v158, v80
	s_and_saveexec_b64 s[46:47], s[2:3]
	s_cbranch_execz .LBB0_274
	v_lshl_add_u64 v[82:83], v[144:145], 2, s[14:15]
	s_waitcnt lgkmcnt(0)
	v_add_f32_e32 v80, v80, v81
	global_atomic_add_f32 v[82:83], v80, off offset:128

.LBB0_275:
	v_or_b32_e32 v80, 48, v144
	s_waitcnt lgkmcnt(0)
	v_ashrrev_i32_e32 v81, 31, v80
	v_lshlrev_b64 v[80:81], 11, v[80:81]
	v_lshl_add_u64 v[86:87], v[80:81], 0, v[146:147]
	v_lshl_add_u64 v[84:85], v[86:87], 2, s[18:19]
	global_load_dwordx4 v[88:91], v[84:85], off
	global_load_dwordx4 v[92:95], v[84:85], off offset:16
	s_and_b64 vcc, exec, s[6:7]
	v_lshl_add_u64 v[82:83], v[86:87], 2, s[12:13]
	s_waitcnt vmcnt(1)
	v_pk_fma_f32 v[78:79], v[78:79], 0.5, v[90:91] op_sel_hi:[1,0,1]
	v_pk_fma_f32 v[76:77], v[76:77], 0.5, v[88:89] op_sel_hi:[1,0,1]
	s_waitcnt vmcnt(0)
	v_pk_fma_f32 v[74:75], v[74:75], 0.5, v[94:95] op_sel_hi:[1,0,1]
	v_pk_fma_f32 v[72:73], v[72:73], 0.5, v[92:93] op_sel_hi:[1,0,1]
	s_cbranch_vccnz .LBB0_277
	global_store_dwordx4 v[82:83], v[76:79], off sc1
	global_store_dwordx4 v[82:83], v[72:75], off offset:16 sc1
.LBB0_277:
	v_lshl_add_u64 v[86:87], v[86:87], 1, s[34:35]
	v_cvt_pk_bf16_f32 v88, v76, v77
	v_cvt_pk_bf16_f32 v89, v78, v79
	v_cvt_pk_bf16_f32 v90, v72, v73
	v_cvt_pk_bf16_f32 v91, v74, v75
	global_store_dwordx4 v[86:87], v[88:91], off sc1
	global_load_dwordx4 v[86:89], v[84:85], off offset:512
	s_nop 0
	global_load_dwordx4 v[90:93], v[84:85], off offset:528
	s_and_b64 vcc, exec, s[6:7]
	s_waitcnt vmcnt(1)
	v_pk_fma_f32 v[70:71], v[70:71], 0.5, v[88:89] op_sel_hi:[1,0,1]
	v_pk_fma_f32 v[68:69], v[68:69], 0.5, v[86:87] op_sel_hi:[1,0,1]
	s_waitcnt vmcnt(0)
	v_pk_fma_f32 v[66:67], v[66:67], 0.5, v[92:93] op_sel_hi:[1,0,1]
	v_pk_fma_f32 v[64:65], v[64:65], 0.5, v[90:91] op_sel_hi:[1,0,1]
	s_cbranch_vccnz .LBB0_279
	global_store_dwordx4 v[82:83], v[68:71], off offset:512 sc1
	global_store_dwordx4 v[82:83], v[64:67], off offset:528 sc1
.LBB0_279:
	v_lshl_add_u64 v[84:85], v[80:81], 0, v[148:149]
	v_lshl_add_u64 v[84:85], v[84:85], 1, s[34:35]
	s_and_b64 vcc, exec, s[8:9]
	v_cvt_pk_bf16_f32 v80, v68, v69
	v_cvt_pk_bf16_f32 v81, v70, v71
	v_cvt_pk_bf16_f32 v82, v64, v65
	v_cvt_pk_bf16_f32 v83, v66, v67
	global_store_dwordx4 v[84:85], v[80:83], off sc1
	s_cbranch_vccnz .LBB0_283
	v_mul_f32_e32 v77, v77, v77
	v_mul_f32_e32 v73, v73, v73
	v_mul_f32_e32 v69, v69, v69
	v_mul_f32_e32 v65, v65, v65
	v_fmac_f32_e32 v77, v76, v76
	v_mul_f32_e32 v76, v79, v79
	v_fmac_f32_e32 v73, v72, v72
	v_mul_f32_e32 v72, v75, v75
	v_fmac_f32_e32 v69, v68, v68
	v_mul_f32_e32 v68, v71, v71
	v_fmac_f32_e32 v65, v64, v64
	v_mul_f32_e32 v64, v67, v67
	v_fmac_f32_e32 v76, v78, v78
	v_fmac_f32_e32 v72, v74, v74
	v_fmac_f32_e32 v68, v70, v70
	v_fmac_f32_e32 v64, v66, v66
	v_add_f32_e32 v76, v77, v76
	v_add_f32_e32 v72, v73, v72
	v_add_f32_e32 v68, v69, v68
	v_add_f32_e32 v64, v65, v64
	v_add_f32_e32 v72, v76, v72
	v_add_f32_e32 v64, v68, v64
	v_add_f32_e32 v64, v72, v64
	ds_bpermute_b32 v65, v157, v64
	s_waitcnt lgkmcnt(0)
	v_add_f32_e32 v64, v64, v65
	ds_bpermute_b32 v65, v158, v64
	s_and_saveexec_b64 s[46:47], s[2:3]
	s_cbranch_execz .LBB0_282
	v_lshl_add_u64 v[66:67], v[144:145], 2, s[14:15]
	s_waitcnt lgkmcnt(0)
	v_add_f32_e32 v64, v64, v65
	global_atomic_add_f32 v[66:67], v64, off offset:192

.LBB0_283:
	v_or_b32_e32 v64, 0x80, v144
	s_waitcnt lgkmcnt(0)
	v_ashrrev_i32_e32 v65, 31, v64
	v_lshlrev_b64 v[64:65], 11, v[64:65]
	v_lshl_add_u64 v[70:71], v[64:65], 0, v[146:147]
	v_lshl_add_u64 v[68:69], v[70:71], 2, s[18:19]
	global_load_dwordx4 v[72:75], v[68:69], off
	global_load_dwordx4 v[76:79], v[68:69], off offset:16
	s_and_b64 vcc, exec, s[6:7]
	v_lshl_add_u64 v[66:67], v[70:71], 2, s[12:13]
	s_waitcnt vmcnt(1)
	v_pk_fma_f32 v[62:63], v[62:63], 0.5, v[74:75] op_sel_hi:[1,0,1]
	v_pk_fma_f32 v[60:61], v[60:61], 0.5, v[72:73] op_sel_hi:[1,0,1]
	s_waitcnt vmcnt(0)
	v_pk_fma_f32 v[58:59], v[58:59], 0.5, v[78:79] op_sel_hi:[1,0,1]
	v_pk_fma_f32 v[56:57], v[56:57], 0.5, v[76:77] op_sel_hi:[1,0,1]
	s_cbranch_vccnz .LBB0_285
	global_store_dwordx4 v[66:67], v[60:63], off sc1
	global_store_dwordx4 v[66:67], v[56:59], off offset:16 sc1
.LBB0_285:
	v_lshl_add_u64 v[70:71], v[70:71], 1, s[34:35]
	v_cvt_pk_bf16_f32 v72, v60, v61
	v_cvt_pk_bf16_f32 v73, v62, v63
	v_cvt_pk_bf16_f32 v74, v56, v57
	v_cvt_pk_bf16_f32 v75, v58, v59
	global_store_dwordx4 v[70:71], v[72:75], off sc1
	global_load_dwordx4 v[70:73], v[68:69], off offset:512
	s_nop 0
	global_load_dwordx4 v[74:77], v[68:69], off offset:528
	s_and_b64 vcc, exec, s[6:7]
	s_waitcnt vmcnt(1)
	v_pk_fma_f32 v[54:55], v[54:55], 0.5, v[72:73] op_sel_hi:[1,0,1]
	v_pk_fma_f32 v[52:53], v[52:53], 0.5, v[70:71] op_sel_hi:[1,0,1]
	s_waitcnt vmcnt(0)
	v_pk_fma_f32 v[50:51], v[50:51], 0.5, v[76:77] op_sel_hi:[1,0,1]
	v_pk_fma_f32 v[48:49], v[48:49], 0.5, v[74:75] op_sel_hi:[1,0,1]
	s_cbranch_vccnz .LBB0_287
	global_store_dwordx4 v[66:67], v[52:55], off offset:512 sc1
	global_store_dwordx4 v[66:67], v[48:51], off offset:528 sc1
.LBB0_287:
	v_lshl_add_u64 v[68:69], v[64:65], 0, v[148:149]
	v_lshl_add_u64 v[68:69], v[68:69], 1, s[34:35]
	s_and_b64 vcc, exec, s[8:9]
	v_cvt_pk_bf16_f32 v64, v52, v53
	v_cvt_pk_bf16_f32 v65, v54, v55
	v_cvt_pk_bf16_f32 v66, v48, v49
	v_cvt_pk_bf16_f32 v67, v50, v51
	global_store_dwordx4 v[68:69], v[64:67], off sc1
	s_cbranch_vccnz .LBB0_291
	v_mul_f32_e32 v61, v61, v61
	v_mul_f32_e32 v57, v57, v57
	v_mul_f32_e32 v53, v53, v53
	v_mul_f32_e32 v49, v49, v49
	v_fmac_f32_e32 v61, v60, v60
	v_mul_f32_e32 v60, v63, v63
	v_fmac_f32_e32 v57, v56, v56
	v_mul_f32_e32 v56, v59, v59
	v_fmac_f32_e32 v53, v52, v52
	v_mul_f32_e32 v52, v55, v55
	v_fmac_f32_e32 v49, v48, v48
	v_mul_f32_e32 v48, v51, v51
	v_fmac_f32_e32 v60, v62, v62
	v_fmac_f32_e32 v56, v58, v58
	v_fmac_f32_e32 v52, v54, v54
	v_fmac_f32_e32 v48, v50, v50
	v_add_f32_e32 v60, v61, v60
	v_add_f32_e32 v56, v57, v56
	v_add_f32_e32 v52, v53, v52
	v_add_f32_e32 v48, v49, v48
	v_add_f32_e32 v56, v60, v56
	v_add_f32_e32 v48, v52, v48
	v_add_f32_e32 v48, v56, v48
	ds_bpermute_b32 v49, v157, v48
	s_waitcnt lgkmcnt(0)
	v_add_f32_e32 v48, v48, v49
	ds_bpermute_b32 v49, v158, v48
	s_and_saveexec_b64 s[46:47], s[2:3]
	s_cbranch_execz .LBB0_290
	v_lshl_add_u64 v[50:51], v[144:145], 2, s[14:15]
	s_waitcnt lgkmcnt(0)
	v_add_f32_e32 v48, v48, v49
	global_atomic_add_f32 v[50:51], v48, off offset:512

.LBB0_291:
	v_or_b32_e32 v48, 0x90, v144
	s_waitcnt lgkmcnt(0)
	v_ashrrev_i32_e32 v49, 31, v48
	v_lshlrev_b64 v[48:49], 11, v[48:49]
	v_lshl_add_u64 v[54:55], v[48:49], 0, v[146:147]
	v_lshl_add_u64 v[52:53], v[54:55], 2, s[18:19]
	global_load_dwordx4 v[56:59], v[52:53], off
	global_load_dwordx4 v[60:63], v[52:53], off offset:16
	s_and_b64 vcc, exec, s[6:7]
	v_lshl_add_u64 v[50:51], v[54:55], 2, s[12:13]
	s_waitcnt vmcnt(1)
	v_pk_fma_f32 v[46:47], v[46:47], 0.5, v[58:59] op_sel_hi:[1,0,1]
	v_pk_fma_f32 v[44:45], v[44:45], 0.5, v[56:57] op_sel_hi:[1,0,1]
	s_waitcnt vmcnt(0)
	v_pk_fma_f32 v[42:43], v[42:43], 0.5, v[62:63] op_sel_hi:[1,0,1]
	v_pk_fma_f32 v[40:41], v[40:41], 0.5, v[60:61] op_sel_hi:[1,0,1]
	s_cbranch_vccnz .LBB0_293
	global_store_dwordx4 v[50:51], v[44:47], off sc1
	global_store_dwordx4 v[50:51], v[40:43], off offset:16 sc1
.LBB0_293:
	v_lshl_add_u64 v[54:55], v[54:55], 1, s[34:35]
	v_cvt_pk_bf16_f32 v56, v44, v45
	v_cvt_pk_bf16_f32 v57, v46, v47
	v_cvt_pk_bf16_f32 v58, v40, v41
	v_cvt_pk_bf16_f32 v59, v42, v43
	global_store_dwordx4 v[54:55], v[56:59], off sc1
	global_load_dwordx4 v[54:57], v[52:53], off offset:512
	s_nop 0
	global_load_dwordx4 v[58:61], v[52:53], off offset:528
	s_and_b64 vcc, exec, s[6:7]
	s_waitcnt vmcnt(1)
	v_pk_fma_f32 v[38:39], v[38:39], 0.5, v[56:57] op_sel_hi:[1,0,1]
	v_pk_fma_f32 v[36:37], v[36:37], 0.5, v[54:55] op_sel_hi:[1,0,1]
	s_waitcnt vmcnt(0)
	v_pk_fma_f32 v[34:35], v[34:35], 0.5, v[60:61] op_sel_hi:[1,0,1]
	v_pk_fma_f32 v[32:33], v[32:33], 0.5, v[58:59] op_sel_hi:[1,0,1]
	s_cbranch_vccnz .LBB0_295
	global_store_dwordx4 v[50:51], v[36:39], off offset:512 sc1
	global_store_dwordx4 v[50:51], v[32:35], off offset:528 sc1
.LBB0_295:
	v_lshl_add_u64 v[52:53], v[48:49], 0, v[148:149]
	v_lshl_add_u64 v[52:53], v[52:53], 1, s[34:35]
	s_and_b64 vcc, exec, s[8:9]
	v_cvt_pk_bf16_f32 v48, v36, v37
	v_cvt_pk_bf16_f32 v49, v38, v39
	v_cvt_pk_bf16_f32 v50, v32, v33
	v_cvt_pk_bf16_f32 v51, v34, v35
	global_store_dwordx4 v[52:53], v[48:51], off sc1
	s_cbranch_vccnz .LBB0_299
	v_mul_f32_e32 v45, v45, v45
	v_mul_f32_e32 v41, v41, v41
	v_mul_f32_e32 v37, v37, v37
	v_mul_f32_e32 v33, v33, v33
	v_fmac_f32_e32 v45, v44, v44
	v_mul_f32_e32 v44, v47, v47
	v_fmac_f32_e32 v41, v40, v40
	v_mul_f32_e32 v40, v43, v43
	v_fmac_f32_e32 v37, v36, v36
	v_mul_f32_e32 v36, v39, v39
	v_fmac_f32_e32 v33, v32, v32
	v_mul_f32_e32 v32, v35, v35
	v_fmac_f32_e32 v44, v46, v46
	v_fmac_f32_e32 v40, v42, v42
	v_fmac_f32_e32 v36, v38, v38
	v_fmac_f32_e32 v32, v34, v34
	v_add_f32_e32 v44, v45, v44
	v_add_f32_e32 v40, v41, v40
	v_add_f32_e32 v36, v37, v36
	v_add_f32_e32 v32, v33, v32
	v_add_f32_e32 v40, v44, v40
	v_add_f32_e32 v32, v36, v32
	v_add_f32_e32 v32, v40, v32
	ds_bpermute_b32 v33, v157, v32
	s_waitcnt lgkmcnt(0)
	v_add_f32_e32 v32, v32, v33
	ds_bpermute_b32 v33, v158, v32
	s_and_saveexec_b64 s[46:47], s[2:3]
	s_cbranch_execz .LBB0_298
	v_lshl_add_u64 v[34:35], v[144:145], 2, s[14:15]
	s_waitcnt lgkmcnt(0)
	v_add_f32_e32 v32, v32, v33
	global_atomic_add_f32 v[34:35], v32, off offset:576

.LBB0_299:
	v_or_b32_e32 v32, 0xa0, v144
	s_waitcnt lgkmcnt(0)
	v_ashrrev_i32_e32 v33, 31, v32
	v_lshlrev_b64 v[32:33], 11, v[32:33]
	v_lshl_add_u64 v[38:39], v[32:33], 0, v[146:147]
	v_lshl_add_u64 v[36:37], v[38:39], 2, s[18:19]
	global_load_dwordx4 v[40:43], v[36:37], off
	global_load_dwordx4 v[44:47], v[36:37], off offset:16
	s_and_b64 vcc, exec, s[6:7]
	v_lshl_add_u64 v[34:35], v[38:39], 2, s[12:13]
	s_waitcnt vmcnt(1)
	v_pk_fma_f32 v[30:31], v[30:31], 0.5, v[42:43] op_sel_hi:[1,0,1]
	v_pk_fma_f32 v[28:29], v[28:29], 0.5, v[40:41] op_sel_hi:[1,0,1]
	s_waitcnt vmcnt(0)
	v_pk_fma_f32 v[26:27], v[26:27], 0.5, v[46:47] op_sel_hi:[1,0,1]
	v_pk_fma_f32 v[24:25], v[24:25], 0.5, v[44:45] op_sel_hi:[1,0,1]
	s_cbranch_vccnz .LBB0_301
	global_store_dwordx4 v[34:35], v[28:31], off sc1
	global_store_dwordx4 v[34:35], v[24:27], off offset:16 sc1
.LBB0_301:
	v_lshl_add_u64 v[38:39], v[38:39], 1, s[34:35]
	v_cvt_pk_bf16_f32 v40, v28, v29
	v_cvt_pk_bf16_f32 v41, v30, v31
	v_cvt_pk_bf16_f32 v42, v24, v25
	v_cvt_pk_bf16_f32 v43, v26, v27
	global_store_dwordx4 v[38:39], v[40:43], off sc1
	global_load_dwordx4 v[38:41], v[36:37], off offset:512
	s_nop 0
	global_load_dwordx4 v[42:45], v[36:37], off offset:528
	s_and_b64 vcc, exec, s[6:7]
	s_waitcnt vmcnt(1)
	v_pk_fma_f32 v[22:23], v[22:23], 0.5, v[40:41] op_sel_hi:[1,0,1]
	v_pk_fma_f32 v[20:21], v[20:21], 0.5, v[38:39] op_sel_hi:[1,0,1]
	s_waitcnt vmcnt(0)
	v_pk_fma_f32 v[18:19], v[18:19], 0.5, v[44:45] op_sel_hi:[1,0,1]
	v_pk_fma_f32 v[16:17], v[16:17], 0.5, v[42:43] op_sel_hi:[1,0,1]
	s_cbranch_vccnz .LBB0_303
	global_store_dwordx4 v[34:35], v[20:23], off offset:512 sc1
	global_store_dwordx4 v[34:35], v[16:19], off offset:528 sc1
.LBB0_303:
	v_lshl_add_u64 v[36:37], v[32:33], 0, v[148:149]
	v_lshl_add_u64 v[36:37], v[36:37], 1, s[34:35]
	s_and_b64 vcc, exec, s[8:9]
	v_cvt_pk_bf16_f32 v32, v20, v21
	v_cvt_pk_bf16_f32 v33, v22, v23
	v_cvt_pk_bf16_f32 v34, v16, v17
	v_cvt_pk_bf16_f32 v35, v18, v19
	global_store_dwordx4 v[36:37], v[32:35], off sc1
	s_cbranch_vccnz .LBB0_307
	v_mul_f32_e32 v29, v29, v29
	v_mul_f32_e32 v25, v25, v25
	v_mul_f32_e32 v21, v21, v21
	v_mul_f32_e32 v17, v17, v17
	v_fmac_f32_e32 v29, v28, v28
	v_mul_f32_e32 v28, v31, v31
	v_fmac_f32_e32 v25, v24, v24
	v_mul_f32_e32 v24, v27, v27
	v_fmac_f32_e32 v21, v20, v20
	v_mul_f32_e32 v20, v23, v23
	v_fmac_f32_e32 v17, v16, v16
	v_mul_f32_e32 v16, v19, v19
	v_fmac_f32_e32 v28, v30, v30
	v_fmac_f32_e32 v24, v26, v26
	v_fmac_f32_e32 v20, v22, v22
	v_fmac_f32_e32 v16, v18, v18
	v_add_f32_e32 v28, v29, v28
	v_add_f32_e32 v24, v25, v24
	v_add_f32_e32 v20, v21, v20
	v_add_f32_e32 v16, v17, v16
	v_add_f32_e32 v24, v28, v24
	v_add_f32_e32 v16, v20, v16
	v_add_f32_e32 v16, v24, v16
	ds_bpermute_b32 v17, v157, v16
	s_waitcnt lgkmcnt(0)
	v_add_f32_e32 v16, v16, v17
	ds_bpermute_b32 v17, v158, v16
	s_and_saveexec_b64 s[46:47], s[2:3]
	s_cbranch_execz .LBB0_306
	v_lshl_add_u64 v[18:19], v[144:145], 2, s[14:15]
	s_waitcnt lgkmcnt(0)
	v_add_f32_e32 v16, v16, v17
	global_atomic_add_f32 v[18:19], v16, off offset:640

.LBB0_307:
	v_or_b32_e32 v16, 0xb0, v144
	s_waitcnt lgkmcnt(0)
	v_ashrrev_i32_e32 v17, 31, v16
	v_lshlrev_b64 v[16:17], 11, v[16:17]
	v_lshl_add_u64 v[22:23], v[16:17], 0, v[146:147]
	v_lshl_add_u64 v[20:21], v[22:23], 2, s[18:19]
	global_load_dwordx4 v[24:27], v[20:21], off
	global_load_dwordx4 v[28:31], v[20:21], off offset:16
	s_and_b64 vcc, exec, s[6:7]
	v_lshl_add_u64 v[18:19], v[22:23], 2, s[12:13]
	s_waitcnt vmcnt(1)
	v_pk_fma_f32 v[14:15], v[14:15], 0.5, v[26:27] op_sel_hi:[1,0,1]
	v_pk_fma_f32 v[12:13], v[12:13], 0.5, v[24:25] op_sel_hi:[1,0,1]
	s_waitcnt vmcnt(0)
	v_pk_fma_f32 v[10:11], v[10:11], 0.5, v[30:31] op_sel_hi:[1,0,1]
	v_pk_fma_f32 v[8:9], v[8:9], 0.5, v[28:29] op_sel_hi:[1,0,1]
	s_cbranch_vccnz .LBB0_309
	global_store_dwordx4 v[18:19], v[12:15], off sc1
	global_store_dwordx4 v[18:19], v[8:11], off offset:16 sc1
.LBB0_309:
	v_lshl_add_u64 v[22:23], v[22:23], 1, s[34:35]
	v_cvt_pk_bf16_f32 v24, v12, v13
	v_cvt_pk_bf16_f32 v25, v14, v15
	v_cvt_pk_bf16_f32 v26, v8, v9
	v_cvt_pk_bf16_f32 v27, v10, v11
	global_store_dwordx4 v[22:23], v[24:27], off sc1
	global_load_dwordx4 v[22:25], v[20:21], off offset:512
	s_nop 0
	global_load_dwordx4 v[26:29], v[20:21], off offset:528
	s_and_b64 vcc, exec, s[6:7]
	s_waitcnt vmcnt(1)
	v_pk_fma_f32 v[6:7], v[6:7], 0.5, v[24:25] op_sel_hi:[1,0,1]
	v_pk_fma_f32 v[4:5], v[4:5], 0.5, v[22:23] op_sel_hi:[1,0,1]
	s_waitcnt vmcnt(0)
	v_pk_fma_f32 v[2:3], v[2:3], 0.5, v[28:29] op_sel_hi:[1,0,1]
	v_pk_fma_f32 v[0:1], v[0:1], 0.5, v[26:27] op_sel_hi:[1,0,1]
	s_cbranch_vccnz .LBB0_311
	global_store_dwordx4 v[18:19], v[4:7], off offset:512 sc1
	global_store_dwordx4 v[18:19], v[0:3], off offset:528 sc1
.LBB0_311:
	v_lshl_add_u64 v[20:21], v[16:17], 0, v[148:149]
	v_lshl_add_u64 v[20:21], v[20:21], 1, s[34:35]
	s_and_b64 vcc, exec, s[8:9]
	v_cvt_pk_bf16_f32 v16, v4, v5
	v_cvt_pk_bf16_f32 v17, v6, v7
	v_cvt_pk_bf16_f32 v18, v0, v1
	v_cvt_pk_bf16_f32 v19, v2, v3
	global_store_dwordx4 v[20:21], v[16:19], off sc1
	s_cbranch_vccnz .LBB0_315
	v_mul_f32_e32 v13, v13, v13
	v_mul_f32_e32 v9, v9, v9
	v_mul_f32_e32 v5, v5, v5
	v_mul_f32_e32 v1, v1, v1
	v_fmac_f32_e32 v13, v12, v12
	v_mul_f32_e32 v12, v15, v15
	v_fmac_f32_e32 v9, v8, v8
	v_mul_f32_e32 v8, v11, v11
	v_fmac_f32_e32 v5, v4, v4
	v_mul_f32_e32 v4, v7, v7
	v_fmac_f32_e32 v1, v0, v0
	v_mul_f32_e32 v0, v3, v3
	v_fmac_f32_e32 v12, v14, v14
	v_fmac_f32_e32 v8, v10, v10
	v_fmac_f32_e32 v4, v6, v6
	v_fmac_f32_e32 v0, v2, v2
	v_add_f32_e32 v12, v13, v12
	v_add_f32_e32 v8, v9, v8
	v_add_f32_e32 v4, v5, v4
	v_add_f32_e32 v0, v1, v0
	v_add_f32_e32 v8, v12, v8
	v_add_f32_e32 v0, v4, v0
	v_add_f32_e32 v0, v8, v0
	ds_bpermute_b32 v1, v157, v0
	s_waitcnt lgkmcnt(0)
	v_add_f32_e32 v0, v0, v1
	ds_bpermute_b32 v1, v158, v0
	s_and_saveexec_b64 s[6:7], s[2:3]
	s_cbranch_execz .LBB0_314
	v_lshl_add_u64 v[2:3], v[144:145], 2, s[14:15]
	s_waitcnt lgkmcnt(0)
	v_add_f32_e32 v0, v0, v1
	global_atomic_add_f32 v[2:3], v0, off offset:704

.LBB0_395:
	v_lshl_or_b32 v146, s16, 8, v155
	v_ashrrev_i32_e32 v147, 31, v146
	v_lshl_add_u64 v[150:151], v[146:147], 2, s[12:13]
	global_load_dword v147, v[150:151], off
	s_add_u32 s40, s40, s57
	s_addc_u32 s41, s41, 0
	v_mad_i64_i32 v[160:161], s[42:43], s36, v146, 0
	v_lshl_add_u64 v[148:149], s[40:41], 0, v[136:137]
	s_lshl_b32 s16, s38, 1
	v_lshl_add_u64 v[160:161], v[160:161], 1, v[148:149]
	v_lshl_add_u64 v[164:165], v[160:161], 0, s[16:17]
	s_andn2_b64 vcc, exec, s[2:3]
	s_mov_b64 s[2:3], -1
	s_waitcnt vmcnt(0)
	v_fmamk_f32 v147, v147, 0x3a000000, v159
	v_rsq_f32_e32 v162, v147
	s_nop 0
	v_pk_mul_f32 v[126:127], v[126:127], v[162:163] op_sel_hi:[1,0]
	v_pk_mul_f32 v[124:125], v[124:125], v[162:163] op_sel_hi:[1,0]
	v_pk_mul_f32 v[122:123], v[122:123], v[162:163] op_sel_hi:[1,0]
	v_pk_mul_f32 v[120:121], v[120:121], v[162:163] op_sel_hi:[1,0]
	v_pk_mul_f32 v[118:119], v[118:119], v[162:163] op_sel_hi:[1,0]
	v_pk_mul_f32 v[116:117], v[116:117], v[162:163] op_sel_hi:[1,0]
	v_pk_mul_f32 v[166:167], v[114:115], v[162:163] op_sel_hi:[1,0]
	v_pk_mul_f32 v[162:163], v[112:113], v[162:163] op_sel_hi:[1,0]
	v_cvt_pk_bf16_f32 v112, v124, v125
	v_cvt_pk_bf16_f32 v113, v126, v127
	v_cvt_pk_bf16_f32 v114, v120, v121
	v_cvt_pk_bf16_f32 v115, v122, v123
	global_store_dwordx4 v[160:161], v[112:115], off sc1
	s_nop 1
	v_cvt_pk_bf16_f32 v112, v116, v117
	v_cvt_pk_bf16_f32 v113, v118, v119
	v_cvt_pk_bf16_f32 v114, v162, v163
	v_cvt_pk_bf16_f32 v115, v166, v167
	global_store_dwordx4 v[164:165], v[112:115], off sc1
	global_load_dword v112, v[150:151], off offset:64
	s_nop 0
	v_or_b32_e32 v113, 16, v146
	v_mad_i64_i32 v[114:115], s[38:39], s36, v113, 0
	v_lshl_add_u64 v[114:115], v[114:115], 1, v[148:149]
	v_lshl_add_u64 v[116:117], v[114:115], 0, s[16:17]
	s_waitcnt vmcnt(0)
	v_fmamk_f32 v112, v112, 0x3a000000, v159
	v_rsq_f32_e32 v112, v112
	s_nop 0
	v_pk_mul_f32 v[110:111], v[110:111], v[112:113] op_sel_hi:[1,0]
	v_pk_mul_f32 v[108:109], v[108:109], v[112:113] op_sel_hi:[1,0]
	v_pk_mul_f32 v[106:107], v[106:107], v[112:113] op_sel_hi:[1,0]
	v_pk_mul_f32 v[104:105], v[104:105], v[112:113] op_sel_hi:[1,0]
	v_pk_mul_f32 v[102:103], v[102:103], v[112:113] op_sel_hi:[1,0]
	v_pk_mul_f32 v[100:101], v[100:101], v[112:113] op_sel_hi:[1,0]
	v_pk_mul_f32 v[118:119], v[98:99], v[112:113] op_sel_hi:[1,0]
	v_pk_mul_f32 v[112:113], v[96:97], v[112:113] op_sel_hi:[1,0]
	v_cvt_pk_bf16_f32 v96, v108, v109
	v_cvt_pk_bf16_f32 v97, v110, v111
	v_cvt_pk_bf16_f32 v98, v104, v105
	v_cvt_pk_bf16_f32 v99, v106, v107
	global_store_dwordx4 v[114:115], v[96:99], off sc1
	s_nop 1
	v_cvt_pk_bf16_f32 v96, v100, v101
	v_cvt_pk_bf16_f32 v97, v102, v103
	v_cvt_pk_bf16_f32 v98, v112, v113
	v_cvt_pk_bf16_f32 v99, v118, v119
	global_store_dwordx4 v[116:117], v[96:99], off sc1
	global_load_dword v96, v[150:151], off offset:128
	s_nop 0
	v_or_b32_e32 v97, 32, v146
	v_mad_i64_i32 v[98:99], s[38:39], s36, v97, 0
	v_lshl_add_u64 v[98:99], v[98:99], 1, v[148:149]
	v_lshl_add_u64 v[100:101], v[98:99], 0, s[16:17]
	s_waitcnt vmcnt(0)
	v_fmamk_f32 v96, v96, 0x3a000000, v159
	v_rsq_f32_e32 v96, v96
	s_nop 0
	v_pk_mul_f32 v[94:95], v[94:95], v[96:97] op_sel_hi:[1,0]
	v_pk_mul_f32 v[92:93], v[92:93], v[96:97] op_sel_hi:[1,0]
	v_pk_mul_f32 v[90:91], v[90:91], v[96:97] op_sel_hi:[1,0]
	v_pk_mul_f32 v[88:89], v[88:89], v[96:97] op_sel_hi:[1,0]
	v_pk_mul_f32 v[86:87], v[86:87], v[96:97] op_sel_hi:[1,0]
	v_pk_mul_f32 v[84:85], v[84:85], v[96:97] op_sel_hi:[1,0]
	v_pk_mul_f32 v[102:103], v[82:83], v[96:97] op_sel_hi:[1,0]
	v_pk_mul_f32 v[96:97], v[80:81], v[96:97] op_sel_hi:[1,0]
	v_cvt_pk_bf16_f32 v80, v92, v93
	v_cvt_pk_bf16_f32 v81, v94, v95
	v_cvt_pk_bf16_f32 v82, v88, v89
	v_cvt_pk_bf16_f32 v83, v90, v91
	global_store_dwordx4 v[98:99], v[80:83], off sc1
	s_nop 1
	v_cvt_pk_bf16_f32 v80, v84, v85
	v_cvt_pk_bf16_f32 v81, v86, v87
	v_cvt_pk_bf16_f32 v82, v96, v97
	v_cvt_pk_bf16_f32 v83, v102, v103
	global_store_dwordx4 v[100:101], v[80:83], off sc1
	global_load_dword v80, v[150:151], off offset:192
	s_nop 0
	v_or_b32_e32 v81, 48, v146
	v_mad_i64_i32 v[82:83], s[38:39], s36, v81, 0
	v_lshl_add_u64 v[82:83], v[82:83], 1, v[148:149]
	v_lshl_add_u64 v[84:85], v[82:83], 0, s[16:17]
	s_waitcnt vmcnt(0)
	v_fmamk_f32 v80, v80, 0x3a000000, v159
	v_rsq_f32_e32 v80, v80
	s_nop 0
	v_pk_mul_f32 v[78:79], v[78:79], v[80:81] op_sel_hi:[1,0]
	v_pk_mul_f32 v[76:77], v[76:77], v[80:81] op_sel_hi:[1,0]
	v_pk_mul_f32 v[74:75], v[74:75], v[80:81] op_sel_hi:[1,0]
	v_pk_mul_f32 v[72:73], v[72:73], v[80:81] op_sel_hi:[1,0]
	v_pk_mul_f32 v[70:71], v[70:71], v[80:81] op_sel_hi:[1,0]
	v_pk_mul_f32 v[68:69], v[68:69], v[80:81] op_sel_hi:[1,0]
	v_pk_mul_f32 v[86:87], v[66:67], v[80:81] op_sel_hi:[1,0]
	v_pk_mul_f32 v[80:81], v[64:65], v[80:81] op_sel_hi:[1,0]
	v_cvt_pk_bf16_f32 v64, v76, v77
	v_cvt_pk_bf16_f32 v65, v78, v79
	v_cvt_pk_bf16_f32 v66, v72, v73
	v_cvt_pk_bf16_f32 v67, v74, v75
	global_store_dwordx4 v[82:83], v[64:67], off sc1
	s_nop 1
	v_cvt_pk_bf16_f32 v64, v68, v69
	v_cvt_pk_bf16_f32 v65, v70, v71
	v_cvt_pk_bf16_f32 v66, v80, v81
	v_cvt_pk_bf16_f32 v67, v86, v87
	global_store_dwordx4 v[84:85], v[64:67], off sc1
	global_load_dword v64, v[150:151], off offset:512
	s_nop 0
	v_or_b32_e32 v65, 0x80, v146
	v_mad_i64_i32 v[66:67], s[38:39], s36, v65, 0
	v_lshl_add_u64 v[66:67], v[66:67], 1, v[148:149]
	v_lshl_add_u64 v[68:69], v[66:67], 0, s[16:17]
	s_waitcnt vmcnt(0)
	v_fmamk_f32 v64, v64, 0x3a000000, v159
	v_rsq_f32_e32 v64, v64
	s_nop 0
	v_pk_mul_f32 v[62:63], v[62:63], v[64:65] op_sel_hi:[1,0]
	v_pk_mul_f32 v[60:61], v[60:61], v[64:65] op_sel_hi:[1,0]
	v_pk_mul_f32 v[58:59], v[58:59], v[64:65] op_sel_hi:[1,0]
	v_pk_mul_f32 v[56:57], v[56:57], v[64:65] op_sel_hi:[1,0]
	v_pk_mul_f32 v[54:55], v[54:55], v[64:65] op_sel_hi:[1,0]
	v_pk_mul_f32 v[52:53], v[52:53], v[64:65] op_sel_hi:[1,0]
	v_pk_mul_f32 v[70:71], v[50:51], v[64:65] op_sel_hi:[1,0]
	v_pk_mul_f32 v[64:65], v[48:49], v[64:65] op_sel_hi:[1,0]
	v_cvt_pk_bf16_f32 v48, v60, v61
	v_cvt_pk_bf16_f32 v49, v62, v63
	v_cvt_pk_bf16_f32 v50, v56, v57
	v_cvt_pk_bf16_f32 v51, v58, v59
	global_store_dwordx4 v[66:67], v[48:51], off sc1
	s_nop 1
	v_cvt_pk_bf16_f32 v48, v52, v53
	v_cvt_pk_bf16_f32 v49, v54, v55
	v_cvt_pk_bf16_f32 v50, v64, v65
	v_cvt_pk_bf16_f32 v51, v70, v71
	global_store_dwordx4 v[68:69], v[48:51], off sc1
	global_load_dword v48, v[150:151], off offset:576
	s_nop 0
	v_or_b32_e32 v49, 0x90, v146
	v_mad_i64_i32 v[50:51], s[38:39], s36, v49, 0
	v_lshl_add_u64 v[50:51], v[50:51], 1, v[148:149]
	v_lshl_add_u64 v[52:53], v[50:51], 0, s[16:17]
	s_waitcnt vmcnt(0)
	v_fmamk_f32 v48, v48, 0x3a000000, v159
	v_rsq_f32_e32 v48, v48
	s_nop 0
	v_pk_mul_f32 v[46:47], v[46:47], v[48:49] op_sel_hi:[1,0]
	v_pk_mul_f32 v[44:45], v[44:45], v[48:49] op_sel_hi:[1,0]
	v_pk_mul_f32 v[42:43], v[42:43], v[48:49] op_sel_hi:[1,0]
	v_pk_mul_f32 v[40:41], v[40:41], v[48:49] op_sel_hi:[1,0]
	v_pk_mul_f32 v[38:39], v[38:39], v[48:49] op_sel_hi:[1,0]
	v_pk_mul_f32 v[36:37], v[36:37], v[48:49] op_sel_hi:[1,0]
	v_pk_mul_f32 v[54:55], v[34:35], v[48:49] op_sel_hi:[1,0]
	v_pk_mul_f32 v[48:49], v[32:33], v[48:49] op_sel_hi:[1,0]
	v_cvt_pk_bf16_f32 v32, v44, v45
	v_cvt_pk_bf16_f32 v33, v46, v47
	v_cvt_pk_bf16_f32 v34, v40, v41
	v_cvt_pk_bf16_f32 v35, v42, v43
	global_store_dwordx4 v[50:51], v[32:35], off sc1
	s_nop 1
	v_cvt_pk_bf16_f32 v32, v36, v37
	v_cvt_pk_bf16_f32 v33, v38, v39
	v_cvt_pk_bf16_f32 v34, v48, v49
	v_cvt_pk_bf16_f32 v35, v54, v55
	global_store_dwordx4 v[52:53], v[32:35], off sc1
	global_load_dword v32, v[150:151], off offset:640
	s_nop 0
	v_or_b32_e32 v33, 0xa0, v146
	v_mad_i64_i32 v[34:35], s[38:39], s36, v33, 0
	v_lshl_add_u64 v[34:35], v[34:35], 1, v[148:149]
	v_lshl_add_u64 v[36:37], v[34:35], 0, s[16:17]
	s_waitcnt vmcnt(0)
	v_fmamk_f32 v32, v32, 0x3a000000, v159
	v_rsq_f32_e32 v32, v32
	s_nop 0
	v_pk_mul_f32 v[30:31], v[30:31], v[32:33] op_sel_hi:[1,0]
	v_pk_mul_f32 v[28:29], v[28:29], v[32:33] op_sel_hi:[1,0]
	v_pk_mul_f32 v[26:27], v[26:27], v[32:33] op_sel_hi:[1,0]
	v_pk_mul_f32 v[24:25], v[24:25], v[32:33] op_sel_hi:[1,0]
	v_pk_mul_f32 v[22:23], v[22:23], v[32:33] op_sel_hi:[1,0]
	v_pk_mul_f32 v[20:21], v[20:21], v[32:33] op_sel_hi:[1,0]
	v_pk_mul_f32 v[38:39], v[18:19], v[32:33] op_sel_hi:[1,0]
	v_pk_mul_f32 v[32:33], v[16:17], v[32:33] op_sel_hi:[1,0]
	v_cvt_pk_bf16_f32 v16, v28, v29
	v_cvt_pk_bf16_f32 v17, v30, v31
	v_cvt_pk_bf16_f32 v18, v24, v25
	v_cvt_pk_bf16_f32 v19, v26, v27
	global_store_dwordx4 v[34:35], v[16:19], off sc1
	s_nop 1
	v_cvt_pk_bf16_f32 v16, v20, v21
	v_cvt_pk_bf16_f32 v17, v22, v23
	v_cvt_pk_bf16_f32 v18, v32, v33
	v_cvt_pk_bf16_f32 v19, v38, v39
	global_store_dwordx4 v[36:37], v[16:19], off sc1
	global_load_dword v18, v[150:151], off offset:704
	s_nop 0
	v_or_b32_e32 v16, 0xb0, v146
	v_mad_i64_i32 v[16:17], s[36:37], s36, v16, 0
	v_lshl_add_u64 v[16:17], v[16:17], 1, v[148:149]
	v_lshl_add_u64 v[20:21], v[16:17], 0, s[16:17]
	s_waitcnt vmcnt(0)
	v_fmamk_f32 v18, v18, 0x3a000000, v159
	v_rsq_f32_e32 v18, v18
	s_nop 0
	v_pk_mul_f32 v[14:15], v[14:15], v[18:19] op_sel_hi:[1,0]
	v_pk_mul_f32 v[12:13], v[12:13], v[18:19] op_sel_hi:[1,0]
	v_pk_mul_f32 v[10:11], v[10:11], v[18:19] op_sel_hi:[1,0]
	v_pk_mul_f32 v[8:9], v[8:9], v[18:19] op_sel_hi:[1,0]
	v_pk_mul_f32 v[6:7], v[6:7], v[18:19] op_sel_hi:[1,0]
	v_pk_mul_f32 v[4:5], v[4:5], v[18:19] op_sel_hi:[1,0]
	v_pk_mul_f32 v[22:23], v[2:3], v[18:19] op_sel_hi:[1,0]
	v_pk_mul_f32 v[18:19], v[0:1], v[18:19] op_sel_hi:[1,0]
	v_cvt_pk_bf16_f32 v0, v12, v13
	v_cvt_pk_bf16_f32 v1, v14, v15
	v_cvt_pk_bf16_f32 v2, v8, v9
	v_cvt_pk_bf16_f32 v3, v10, v11
	global_store_dwordx4 v[16:17], v[0:3], off sc1
	s_nop 1
	v_cvt_pk_bf16_f32 v0, v4, v5
	v_cvt_pk_bf16_f32 v1, v6, v7
	v_cvt_pk_bf16_f32 v2, v18, v19
	v_cvt_pk_bf16_f32 v3, v22, v23
	global_store_dwordx4 v[20:21], v[0:3], off sc1
	s_cbranch_vccnz .LBB0_383
	s_andn2_b64 vcc, exec, s[6:7]
	s_cbranch_vccnz .LBB0_382
	s_barrier
	s_branch .LBB0_382

.LBB0_1120:
	v_lshl_or_b32 v146, s6, 8, v157
	v_lshl_or_b32 v144, s44, 8, v158
	v_ashrrev_i32_e32 v147, 31, v146
	v_ashrrev_i32_e32 v145, 31, v144
	v_lshlrev_b64 v[148:149], 11, v[146:147]
	v_lshl_add_u64 v[152:153], v[148:149], 0, v[144:145]
	v_lshl_add_u64 v[150:151], v[152:153], 2, s[12:13]
	global_load_dwordx4 v[162:165], v[150:151], off
	global_load_dwordx4 v[166:169], v[150:151], off offset:16
	v_cndmask_b32_e64 v170, 0, 1, s[34:35]
	v_cmp_ne_u32_e64 s[6:7], 1, v170
	s_andn2_b64 vcc, exec, s[34:35]
	s_waitcnt vmcnt(0)
	v_pk_add_f32 v[126:127], v[126:127], v[164:165]
	v_pk_add_f32 v[124:125], v[124:125], v[162:163]
	v_pk_add_f32 v[122:123], v[122:123], v[168:169]
	v_pk_add_f32 v[120:121], v[120:121], v[166:167]
	s_cbranch_vccnz .LBB0_1122
	global_store_dwordx4 v[150:151], v[124:127], off sc1
	global_store_dwordx4 v[150:151], v[120:123], off offset:16 sc1
.LBB0_1122:
	v_lshl_add_u64 v[152:153], v[152:153], 1, s[28:29]
	v_cvt_pk_bf16_f32 v162, v124, v125
	v_cvt_pk_bf16_f32 v163, v126, v127
	v_cvt_pk_bf16_f32 v164, v120, v121
	v_cvt_pk_bf16_f32 v165, v122, v123
	global_store_dwordx4 v[152:153], v[162:165], off sc1
	global_load_dwordx4 v[162:165], v[150:151], off offset:512
	s_nop 0
	global_load_dwordx4 v[166:169], v[150:151], off offset:528
	s_and_b64 vcc, exec, s[6:7]
	s_waitcnt vmcnt(1)
	v_pk_add_f32 v[118:119], v[118:119], v[164:165]
	v_pk_add_f32 v[116:117], v[116:117], v[162:163]
	s_waitcnt vmcnt(0)
	v_pk_add_f32 v[114:115], v[114:115], v[168:169]
	v_pk_add_f32 v[112:113], v[112:113], v[166:167]
	s_cbranch_vccnz .LBB0_1124
	global_store_dwordx4 v[150:151], v[116:119], off offset:512 sc1
	global_store_dwordx4 v[150:151], v[112:115], off offset:528 sc1
.LBB0_1124:
	v_mul_f32_e32 v125, v125, v125
	v_mul_f32_e32 v121, v121, v121
	v_fmac_f32_e32 v125, v124, v124
	v_mul_f32_e32 v124, v127, v127
	v_fmac_f32_e32 v121, v120, v120
	v_mul_f32_e32 v120, v123, v123
	v_fmac_f32_e32 v124, v126, v126
	v_fmac_f32_e32 v120, v122, v122
	v_mul_f32_e32 v122, v117, v117
	v_mul_f32_e32 v123, v119, v119
	v_add_f32_e32 v124, v125, v124
	v_add_f32_e32 v120, v121, v120
	v_fmac_f32_e32 v122, v116, v116
	v_fmac_f32_e32 v123, v118, v118
	v_add_f32_e32 v121, v124, v120
	v_add_f32_e32 v122, v122, v123
	v_mul_f32_e32 v123, v113, v113
	v_mul_f32_e32 v124, v115, v115
	v_fmac_f32_e32 v123, v112, v112
	v_fmac_f32_e32 v124, v114, v114
	v_add_f32_e32 v123, v123, v124
	v_add_f32_e32 v122, v122, v123
	v_add_f32_e32 v124, v121, v122
	ds_bpermute_b32 v125, v155, v124
	v_cvt_pk_bf16_f32 v122, v116, v117
	v_or_b32_e32 v120, 0x80, v144
	v_mov_b32_e32 v121, v145
	v_lshl_add_u64 v[126:127], v[148:149], 0, v[120:121]
	s_waitcnt lgkmcnt(0)
	v_add_f32_e32 v116, v124, v125
	ds_bpermute_b32 v117, v156, v116
	v_cvt_pk_bf16_f32 v123, v118, v119
	v_cvt_pk_bf16_f32 v124, v112, v113
	v_lshl_add_u64 v[112:113], v[126:127], 1, s[28:29]
	v_cvt_pk_bf16_f32 v125, v114, v115
	global_store_dwordx4 v[112:113], v[122:125], off sc1
	s_and_saveexec_b64 s[44:45], s[2:3]
	s_cbranch_execz .LBB0_1126
	v_lshl_add_u64 v[112:113], v[146:147], 2, s[14:15]
	s_waitcnt lgkmcnt(0)
	v_add_f32_e32 v114, v116, v117
	global_atomic_add_f32 v[112:113], v114, off
.LBB0_1126:
	s_or_b64 exec, exec, s[44:45]
	v_or_b32_e32 v112, 16, v146
	v_ashrrev_i32_e32 v113, 31, v112
	v_lshlrev_b64 v[114:115], 11, v[112:113]
	v_lshl_add_u64 v[118:119], v[114:115], 0, v[144:145]
	s_waitcnt lgkmcnt(0)
	v_lshl_add_u64 v[116:117], v[118:119], 2, s[12:13]
	global_load_dwordx4 v[122:125], v[116:117], off
	global_load_dwordx4 v[148:151], v[116:117], off offset:16
	s_and_b64 vcc, exec, s[6:7]
	s_waitcnt vmcnt(1)
	v_pk_add_f32 v[110:111], v[110:111], v[124:125]
	v_pk_add_f32 v[108:109], v[108:109], v[122:123]
	s_waitcnt vmcnt(0)
	v_pk_add_f32 v[106:107], v[106:107], v[150:151]
	v_pk_add_f32 v[104:105], v[104:105], v[148:149]
	s_cbranch_vccnz .LBB0_1128
	global_store_dwordx4 v[116:117], v[108:111], off sc1
	global_store_dwordx4 v[116:117], v[104:107], off offset:16 sc1
.LBB0_1128:
	v_lshl_add_u64 v[118:119], v[118:119], 1, s[28:29]
	v_cvt_pk_bf16_f32 v122, v108, v109
	v_cvt_pk_bf16_f32 v123, v110, v111
	v_cvt_pk_bf16_f32 v124, v104, v105
	v_cvt_pk_bf16_f32 v125, v106, v107
	global_store_dwordx4 v[118:119], v[122:125], off sc1
	global_load_dwordx4 v[122:125], v[116:117], off offset:512
	s_nop 0
	global_load_dwordx4 v[148:151], v[116:117], off offset:528
	s_and_b64 vcc, exec, s[6:7]
	s_waitcnt vmcnt(1)
	v_pk_add_f32 v[102:103], v[102:103], v[124:125]
	v_pk_add_f32 v[100:101], v[100:101], v[122:123]
	s_waitcnt vmcnt(0)
	v_pk_add_f32 v[98:99], v[98:99], v[150:151]
	v_pk_add_f32 v[96:97], v[96:97], v[148:149]
	s_cbranch_vccnz .LBB0_1130
	global_store_dwordx4 v[116:117], v[100:103], off offset:512 sc1
	global_store_dwordx4 v[116:117], v[96:99], off offset:528 sc1
.LBB0_1130:
	v_mul_f32_e32 v105, v105, v105
	v_fmac_f32_e32 v105, v104, v104
	v_mul_f32_e32 v104, v107, v107
	v_fmac_f32_e32 v104, v106, v106
	v_add_f32_e32 v104, v105, v104
	v_mul_f32_e32 v105, v101, v101
	v_mul_f32_e32 v106, v103, v103
	v_mul_f32_e32 v109, v109, v109
	v_fmac_f32_e32 v105, v100, v100
	v_fmac_f32_e32 v106, v102, v102
	v_fmac_f32_e32 v109, v108, v108
	v_mul_f32_e32 v108, v111, v111
	v_add_f32_e32 v105, v105, v106
	v_mul_f32_e32 v106, v97, v97
	v_mul_f32_e32 v107, v99, v99
	v_fmac_f32_e32 v108, v110, v110
	v_fmac_f32_e32 v106, v96, v96
	v_fmac_f32_e32 v107, v98, v98
	v_add_f32_e32 v108, v109, v108
	v_add_f32_e32 v106, v106, v107
	v_add_f32_e32 v104, v108, v104
	v_add_f32_e32 v105, v105, v106
	v_add_f32_e32 v106, v104, v105
	ds_bpermute_b32 v107, v155, v106
	v_cvt_pk_bf16_f32 v104, v100, v101
	v_lshl_add_u64 v[108:109], v[114:115], 0, v[120:121]
	v_cvt_pk_bf16_f32 v105, v102, v103
	s_waitcnt lgkmcnt(0)
	v_add_f32_e32 v100, v106, v107
	ds_bpermute_b32 v101, v156, v100
	v_cvt_pk_bf16_f32 v106, v96, v97
	v_lshl_add_u64 v[96:97], v[108:109], 1, s[28:29]
	v_cvt_pk_bf16_f32 v107, v98, v99
	global_store_dwordx4 v[96:97], v[104:107], off sc1
	s_and_saveexec_b64 s[44:45], s[2:3]
	s_cbranch_execz .LBB0_1132
	v_lshl_add_u64 v[96:97], v[112:113], 2, s[14:15]
	s_waitcnt lgkmcnt(0)
	v_add_f32_e32 v98, v100, v101
	global_atomic_add_f32 v[96:97], v98, off
.LBB0_1132:
	s_or_b64 exec, exec, s[44:45]
	v_or_b32_e32 v96, 32, v146
	v_ashrrev_i32_e32 v97, 31, v96
	v_lshlrev_b64 v[98:99], 11, v[96:97]
	v_lshl_add_u64 v[102:103], v[98:99], 0, v[144:145]
	s_waitcnt lgkmcnt(0)
	v_lshl_add_u64 v[100:101], v[102:103], 2, s[12:13]
	global_load_dwordx4 v[104:107], v[100:101], off
	global_load_dwordx4 v[108:111], v[100:101], off offset:16
	s_and_b64 vcc, exec, s[6:7]
	s_waitcnt vmcnt(1)
	v_pk_add_f32 v[94:95], v[94:95], v[106:107]
	v_pk_add_f32 v[92:93], v[92:93], v[104:105]
	s_waitcnt vmcnt(0)
	v_pk_add_f32 v[90:91], v[90:91], v[110:111]
	v_pk_add_f32 v[88:89], v[88:89], v[108:109]
	s_cbranch_vccnz .LBB0_1134
	global_store_dwordx4 v[100:101], v[92:95], off sc1
	global_store_dwordx4 v[100:101], v[88:91], off offset:16 sc1
.LBB0_1134:
	v_lshl_add_u64 v[102:103], v[102:103], 1, s[28:29]
	v_cvt_pk_bf16_f32 v104, v92, v93
	v_cvt_pk_bf16_f32 v105, v94, v95
	v_cvt_pk_bf16_f32 v106, v88, v89
	v_cvt_pk_bf16_f32 v107, v90, v91
	global_store_dwordx4 v[102:103], v[104:107], off sc1
	global_load_dwordx4 v[102:105], v[100:101], off offset:512
	s_nop 0
	global_load_dwordx4 v[106:109], v[100:101], off offset:528
	s_and_b64 vcc, exec, s[6:7]
	s_waitcnt vmcnt(1)
	v_pk_add_f32 v[86:87], v[86:87], v[104:105]
	v_pk_add_f32 v[84:85], v[84:85], v[102:103]
	s_waitcnt vmcnt(0)
	v_pk_add_f32 v[82:83], v[82:83], v[108:109]
	v_pk_add_f32 v[80:81], v[80:81], v[106:107]
	s_cbranch_vccnz .LBB0_1136
	global_store_dwordx4 v[100:101], v[84:87], off offset:512 sc1
	global_store_dwordx4 v[100:101], v[80:83], off offset:528 sc1
.LBB0_1136:
	v_mul_f32_e32 v89, v89, v89
	v_fmac_f32_e32 v89, v88, v88
	v_mul_f32_e32 v88, v91, v91
	v_fmac_f32_e32 v88, v90, v90
	v_add_f32_e32 v88, v89, v88
	v_mul_f32_e32 v89, v85, v85
	v_mul_f32_e32 v90, v87, v87
	v_mul_f32_e32 v93, v93, v93
	v_fmac_f32_e32 v89, v84, v84
	v_fmac_f32_e32 v90, v86, v86
	v_fmac_f32_e32 v93, v92, v92
	v_mul_f32_e32 v92, v95, v95
	v_add_f32_e32 v89, v89, v90
	v_mul_f32_e32 v90, v81, v81
	v_mul_f32_e32 v91, v83, v83
	v_fmac_f32_e32 v92, v94, v94
	v_fmac_f32_e32 v90, v80, v80
	v_fmac_f32_e32 v91, v82, v82
	v_add_f32_e32 v92, v93, v92
	v_add_f32_e32 v90, v90, v91
	v_add_f32_e32 v88, v92, v88
	v_add_f32_e32 v89, v89, v90
	v_add_f32_e32 v90, v88, v89
	ds_bpermute_b32 v91, v155, v90
	v_cvt_pk_bf16_f32 v88, v84, v85
	v_lshl_add_u64 v[92:93], v[98:99], 0, v[120:121]
	v_cvt_pk_bf16_f32 v89, v86, v87
	s_waitcnt lgkmcnt(0)
	v_add_f32_e32 v84, v90, v91
	ds_bpermute_b32 v85, v156, v84
	v_cvt_pk_bf16_f32 v90, v80, v81
	v_lshl_add_u64 v[80:81], v[92:93], 1, s[28:29]
	v_cvt_pk_bf16_f32 v91, v82, v83
	global_store_dwordx4 v[80:81], v[88:91], off sc1
	s_and_saveexec_b64 s[44:45], s[2:3]
	s_cbranch_execz .LBB0_1138
	v_lshl_add_u64 v[80:81], v[96:97], 2, s[14:15]
	s_waitcnt lgkmcnt(0)
	v_add_f32_e32 v82, v84, v85
	global_atomic_add_f32 v[80:81], v82, off
.LBB0_1138:
	s_or_b64 exec, exec, s[44:45]
	v_or_b32_e32 v80, 48, v146
	v_ashrrev_i32_e32 v81, 31, v80
	v_lshlrev_b64 v[82:83], 11, v[80:81]
	v_lshl_add_u64 v[86:87], v[82:83], 0, v[144:145]
	s_waitcnt lgkmcnt(0)
	v_lshl_add_u64 v[84:85], v[86:87], 2, s[12:13]
	global_load_dwordx4 v[88:91], v[84:85], off
	global_load_dwordx4 v[92:95], v[84:85], off offset:16
	s_and_b64 vcc, exec, s[6:7]
	s_waitcnt vmcnt(1)
	v_pk_add_f32 v[78:79], v[78:79], v[90:91]
	v_pk_add_f32 v[76:77], v[76:77], v[88:89]
	s_waitcnt vmcnt(0)
	v_pk_add_f32 v[74:75], v[74:75], v[94:95]
	v_pk_add_f32 v[72:73], v[72:73], v[92:93]
	s_cbranch_vccnz .LBB0_1140
	global_store_dwordx4 v[84:85], v[76:79], off sc1
	global_store_dwordx4 v[84:85], v[72:75], off offset:16 sc1
.LBB0_1140:
	v_lshl_add_u64 v[86:87], v[86:87], 1, s[28:29]
	v_cvt_pk_bf16_f32 v88, v76, v77
	v_cvt_pk_bf16_f32 v89, v78, v79
	v_cvt_pk_bf16_f32 v90, v72, v73
	v_cvt_pk_bf16_f32 v91, v74, v75
	global_store_dwordx4 v[86:87], v[88:91], off sc1
	global_load_dwordx4 v[86:89], v[84:85], off offset:512
	s_nop 0
	global_load_dwordx4 v[90:93], v[84:85], off offset:528
	s_and_b64 vcc, exec, s[6:7]
	s_waitcnt vmcnt(1)
	v_pk_add_f32 v[70:71], v[70:71], v[88:89]
	v_pk_add_f32 v[68:69], v[68:69], v[86:87]
	s_waitcnt vmcnt(0)
	v_pk_add_f32 v[66:67], v[66:67], v[92:93]
	v_pk_add_f32 v[64:65], v[64:65], v[90:91]
	s_cbranch_vccnz .LBB0_1142
	global_store_dwordx4 v[84:85], v[68:71], off offset:512 sc1
	global_store_dwordx4 v[84:85], v[64:67], off offset:528 sc1
.LBB0_1142:
	v_mul_f32_e32 v73, v73, v73
	v_fmac_f32_e32 v73, v72, v72
	v_mul_f32_e32 v72, v75, v75
	v_fmac_f32_e32 v72, v74, v74
	v_add_f32_e32 v72, v73, v72
	v_mul_f32_e32 v73, v69, v69
	v_mul_f32_e32 v74, v71, v71
	v_mul_f32_e32 v77, v77, v77
	v_fmac_f32_e32 v73, v68, v68
	v_fmac_f32_e32 v74, v70, v70
	v_fmac_f32_e32 v77, v76, v76
	v_mul_f32_e32 v76, v79, v79
	v_add_f32_e32 v73, v73, v74
	v_mul_f32_e32 v74, v65, v65
	v_mul_f32_e32 v75, v67, v67
	v_fmac_f32_e32 v76, v78, v78
	v_fmac_f32_e32 v74, v64, v64
	v_fmac_f32_e32 v75, v66, v66
	v_add_f32_e32 v76, v77, v76
	v_add_f32_e32 v74, v74, v75
	v_add_f32_e32 v72, v76, v72
	v_add_f32_e32 v73, v73, v74
	v_add_f32_e32 v74, v72, v73
	ds_bpermute_b32 v75, v155, v74
	v_cvt_pk_bf16_f32 v72, v68, v69
	v_lshl_add_u64 v[76:77], v[82:83], 0, v[120:121]
	v_cvt_pk_bf16_f32 v73, v70, v71
	s_waitcnt lgkmcnt(0)
	v_add_f32_e32 v68, v74, v75
	ds_bpermute_b32 v69, v156, v68
	v_cvt_pk_bf16_f32 v74, v64, v65
	v_lshl_add_u64 v[64:65], v[76:77], 1, s[28:29]
	v_cvt_pk_bf16_f32 v75, v66, v67
	global_store_dwordx4 v[64:65], v[72:75], off sc1
	s_and_saveexec_b64 s[44:45], s[2:3]
	s_cbranch_execz .LBB0_1144
	v_lshl_add_u64 v[64:65], v[80:81], 2, s[14:15]
	s_waitcnt lgkmcnt(0)
	v_add_f32_e32 v66, v68, v69
	global_atomic_add_f32 v[64:65], v66, off
.LBB0_1144:
	s_or_b64 exec, exec, s[44:45]
	v_or_b32_e32 v64, 0x80, v146
	v_ashrrev_i32_e32 v65, 31, v64
	v_lshlrev_b64 v[66:67], 11, v[64:65]
	v_lshl_add_u64 v[70:71], v[66:67], 0, v[144:145]
	s_waitcnt lgkmcnt(0)
	v_lshl_add_u64 v[68:69], v[70:71], 2, s[12:13]
	global_load_dwordx4 v[72:75], v[68:69], off
	global_load_dwordx4 v[76:79], v[68:69], off offset:16
	s_and_b64 vcc, exec, s[6:7]
	s_waitcnt vmcnt(1)
	v_pk_add_f32 v[62:63], v[62:63], v[74:75]
	v_pk_add_f32 v[60:61], v[60:61], v[72:73]
	s_waitcnt vmcnt(0)
	v_pk_add_f32 v[58:59], v[58:59], v[78:79]
	v_pk_add_f32 v[56:57], v[56:57], v[76:77]
	s_cbranch_vccnz .LBB0_1146
	global_store_dwordx4 v[68:69], v[60:63], off sc1
	global_store_dwordx4 v[68:69], v[56:59], off offset:16 sc1
.LBB0_1146:
	v_lshl_add_u64 v[70:71], v[70:71], 1, s[28:29]
	v_cvt_pk_bf16_f32 v72, v60, v61
	v_cvt_pk_bf16_f32 v73, v62, v63
	v_cvt_pk_bf16_f32 v74, v56, v57
	v_cvt_pk_bf16_f32 v75, v58, v59
	global_store_dwordx4 v[70:71], v[72:75], off sc1
	global_load_dwordx4 v[70:73], v[68:69], off offset:512
	s_nop 0
	global_load_dwordx4 v[74:77], v[68:69], off offset:528
	s_and_b64 vcc, exec, s[6:7]
	s_waitcnt vmcnt(1)
	v_pk_add_f32 v[54:55], v[54:55], v[72:73]
	v_pk_add_f32 v[52:53], v[52:53], v[70:71]
	s_waitcnt vmcnt(0)
	v_pk_add_f32 v[50:51], v[50:51], v[76:77]
	v_pk_add_f32 v[48:49], v[48:49], v[74:75]
	s_cbranch_vccnz .LBB0_1148
	global_store_dwordx4 v[68:69], v[52:55], off offset:512 sc1
	global_store_dwordx4 v[68:69], v[48:51], off offset:528 sc1
.LBB0_1148:
	v_mul_f32_e32 v57, v57, v57
	v_fmac_f32_e32 v57, v56, v56
	v_mul_f32_e32 v56, v59, v59
	v_fmac_f32_e32 v56, v58, v58
	v_add_f32_e32 v56, v57, v56
	v_mul_f32_e32 v57, v53, v53
	v_mul_f32_e32 v58, v55, v55
	v_mul_f32_e32 v61, v61, v61
	v_fmac_f32_e32 v57, v52, v52
	v_fmac_f32_e32 v58, v54, v54
	v_fmac_f32_e32 v61, v60, v60
	v_mul_f32_e32 v60, v63, v63
	v_add_f32_e32 v57, v57, v58
	v_mul_f32_e32 v58, v49, v49
	v_mul_f32_e32 v59, v51, v51
	v_fmac_f32_e32 v60, v62, v62
	v_fmac_f32_e32 v58, v48, v48
	v_fmac_f32_e32 v59, v50, v50
	v_add_f32_e32 v60, v61, v60
	v_add_f32_e32 v58, v58, v59
	v_add_f32_e32 v56, v60, v56
	v_add_f32_e32 v57, v57, v58
	v_add_f32_e32 v58, v56, v57
	ds_bpermute_b32 v59, v155, v58
	v_cvt_pk_bf16_f32 v56, v52, v53
	v_lshl_add_u64 v[60:61], v[66:67], 0, v[120:121]
	v_cvt_pk_bf16_f32 v57, v54, v55
	s_waitcnt lgkmcnt(0)
	v_add_f32_e32 v52, v58, v59
	ds_bpermute_b32 v53, v156, v52
	v_cvt_pk_bf16_f32 v58, v48, v49
	v_lshl_add_u64 v[48:49], v[60:61], 1, s[28:29]
	v_cvt_pk_bf16_f32 v59, v50, v51
	global_store_dwordx4 v[48:49], v[56:59], off sc1
	s_and_saveexec_b64 s[44:45], s[2:3]
	s_cbranch_execz .LBB0_1150
	v_lshl_add_u64 v[48:49], v[64:65], 2, s[14:15]
	s_waitcnt lgkmcnt(0)
	v_add_f32_e32 v50, v52, v53
	global_atomic_add_f32 v[48:49], v50, off
.LBB0_1150:
	s_or_b64 exec, exec, s[44:45]
	v_or_b32_e32 v48, 0x90, v146
	v_ashrrev_i32_e32 v49, 31, v48
	v_lshlrev_b64 v[50:51], 11, v[48:49]
	v_lshl_add_u64 v[54:55], v[50:51], 0, v[144:145]
	s_waitcnt lgkmcnt(0)
	v_lshl_add_u64 v[52:53], v[54:55], 2, s[12:13]
	global_load_dwordx4 v[56:59], v[52:53], off
	global_load_dwordx4 v[60:63], v[52:53], off offset:16
	s_and_b64 vcc, exec, s[6:7]
	s_waitcnt vmcnt(1)
	v_pk_add_f32 v[46:47], v[46:47], v[58:59]
	v_pk_add_f32 v[44:45], v[44:45], v[56:57]
	s_waitcnt vmcnt(0)
	v_pk_add_f32 v[42:43], v[42:43], v[62:63]
	v_pk_add_f32 v[40:41], v[40:41], v[60:61]
	s_cbranch_vccnz .LBB0_1152
	global_store_dwordx4 v[52:53], v[44:47], off sc1
	global_store_dwordx4 v[52:53], v[40:43], off offset:16 sc1
.LBB0_1152:
	v_lshl_add_u64 v[54:55], v[54:55], 1, s[28:29]
	v_cvt_pk_bf16_f32 v56, v44, v45
	v_cvt_pk_bf16_f32 v57, v46, v47
	v_cvt_pk_bf16_f32 v58, v40, v41
	v_cvt_pk_bf16_f32 v59, v42, v43
	global_store_dwordx4 v[54:55], v[56:59], off sc1
	global_load_dwordx4 v[54:57], v[52:53], off offset:512
	s_nop 0
	global_load_dwordx4 v[58:61], v[52:53], off offset:528
	s_and_b64 vcc, exec, s[6:7]
	s_waitcnt vmcnt(1)
	v_pk_add_f32 v[38:39], v[38:39], v[56:57]
	v_pk_add_f32 v[36:37], v[36:37], v[54:55]
	s_waitcnt vmcnt(0)
	v_pk_add_f32 v[34:35], v[34:35], v[60:61]
	v_pk_add_f32 v[32:33], v[32:33], v[58:59]
	s_cbranch_vccnz .LBB0_1154
	global_store_dwordx4 v[52:53], v[36:39], off offset:512 sc1
	global_store_dwordx4 v[52:53], v[32:35], off offset:528 sc1
.LBB0_1154:
	v_mul_f32_e32 v41, v41, v41
	v_fmac_f32_e32 v41, v40, v40
	v_mul_f32_e32 v40, v43, v43
	v_fmac_f32_e32 v40, v42, v42
	v_add_f32_e32 v40, v41, v40
	v_mul_f32_e32 v41, v37, v37
	v_mul_f32_e32 v42, v39, v39
	v_mul_f32_e32 v45, v45, v45
	v_fmac_f32_e32 v41, v36, v36
	v_fmac_f32_e32 v42, v38, v38
	v_fmac_f32_e32 v45, v44, v44
	v_mul_f32_e32 v44, v47, v47
	v_add_f32_e32 v41, v41, v42
	v_mul_f32_e32 v42, v33, v33
	v_mul_f32_e32 v43, v35, v35
	v_fmac_f32_e32 v44, v46, v46
	v_fmac_f32_e32 v42, v32, v32
	v_fmac_f32_e32 v43, v34, v34
	v_add_f32_e32 v44, v45, v44
	v_add_f32_e32 v42, v42, v43
	v_add_f32_e32 v40, v44, v40
	v_add_f32_e32 v41, v41, v42
	v_add_f32_e32 v42, v40, v41
	ds_bpermute_b32 v43, v155, v42
	v_cvt_pk_bf16_f32 v40, v36, v37
	v_lshl_add_u64 v[44:45], v[50:51], 0, v[120:121]
	v_cvt_pk_bf16_f32 v41, v38, v39
	s_waitcnt lgkmcnt(0)
	v_add_f32_e32 v36, v42, v43
	ds_bpermute_b32 v37, v156, v36
	v_cvt_pk_bf16_f32 v42, v32, v33
	v_lshl_add_u64 v[32:33], v[44:45], 1, s[28:29]
	v_cvt_pk_bf16_f32 v43, v34, v35
	global_store_dwordx4 v[32:33], v[40:43], off sc1
	s_and_saveexec_b64 s[44:45], s[2:3]
	s_cbranch_execz .LBB0_1156
	v_lshl_add_u64 v[32:33], v[48:49], 2, s[14:15]
	s_waitcnt lgkmcnt(0)
	v_add_f32_e32 v34, v36, v37
	global_atomic_add_f32 v[32:33], v34, off
.LBB0_1156:
	s_or_b64 exec, exec, s[44:45]
	v_or_b32_e32 v32, 0xa0, v146
	v_ashrrev_i32_e32 v33, 31, v32
	v_lshlrev_b64 v[34:35], 11, v[32:33]
	v_lshl_add_u64 v[38:39], v[34:35], 0, v[144:145]
	s_waitcnt lgkmcnt(0)
	v_lshl_add_u64 v[36:37], v[38:39], 2, s[12:13]
	global_load_dwordx4 v[40:43], v[36:37], off
	global_load_dwordx4 v[44:47], v[36:37], off offset:16
	s_and_b64 vcc, exec, s[6:7]
	s_waitcnt vmcnt(1)
	v_pk_add_f32 v[30:31], v[30:31], v[42:43]
	v_pk_add_f32 v[28:29], v[28:29], v[40:41]
	s_waitcnt vmcnt(0)
	v_pk_add_f32 v[26:27], v[26:27], v[46:47]
	v_pk_add_f32 v[24:25], v[24:25], v[44:45]
	s_cbranch_vccnz .LBB0_1158
	global_store_dwordx4 v[36:37], v[28:31], off sc1
	global_store_dwordx4 v[36:37], v[24:27], off offset:16 sc1
.LBB0_1158:
	v_lshl_add_u64 v[38:39], v[38:39], 1, s[28:29]
	v_cvt_pk_bf16_f32 v40, v28, v29
	v_cvt_pk_bf16_f32 v41, v30, v31
	v_cvt_pk_bf16_f32 v42, v24, v25
	v_cvt_pk_bf16_f32 v43, v26, v27
	global_store_dwordx4 v[38:39], v[40:43], off sc1
	global_load_dwordx4 v[38:41], v[36:37], off offset:512
	s_nop 0
	global_load_dwordx4 v[42:45], v[36:37], off offset:528
	s_and_b64 vcc, exec, s[6:7]
	s_waitcnt vmcnt(1)
	v_pk_add_f32 v[22:23], v[22:23], v[40:41]
	v_pk_add_f32 v[20:21], v[20:21], v[38:39]
	s_waitcnt vmcnt(0)
	v_pk_add_f32 v[18:19], v[18:19], v[44:45]
	v_pk_add_f32 v[16:17], v[16:17], v[42:43]
	s_cbranch_vccnz .LBB0_1160
	global_store_dwordx4 v[36:37], v[20:23], off offset:512 sc1
	global_store_dwordx4 v[36:37], v[16:19], off offset:528 sc1
.LBB0_1160:
	v_mul_f32_e32 v25, v25, v25
	v_fmac_f32_e32 v25, v24, v24
	v_mul_f32_e32 v24, v27, v27
	v_fmac_f32_e32 v24, v26, v26
	v_add_f32_e32 v24, v25, v24
	v_mul_f32_e32 v25, v21, v21
	v_mul_f32_e32 v26, v23, v23
	v_mul_f32_e32 v29, v29, v29
	v_fmac_f32_e32 v25, v20, v20
	v_fmac_f32_e32 v26, v22, v22
	v_fmac_f32_e32 v29, v28, v28
	v_mul_f32_e32 v28, v31, v31
	v_add_f32_e32 v25, v25, v26
	v_mul_f32_e32 v26, v17, v17
	v_mul_f32_e32 v27, v19, v19
	v_fmac_f32_e32 v28, v30, v30
	v_fmac_f32_e32 v26, v16, v16
	v_fmac_f32_e32 v27, v18, v18
	v_add_f32_e32 v28, v29, v28
	v_add_f32_e32 v26, v26, v27
	v_add_f32_e32 v24, v28, v24
	v_add_f32_e32 v25, v25, v26
	v_add_f32_e32 v26, v24, v25
	ds_bpermute_b32 v27, v155, v26
	v_cvt_pk_bf16_f32 v24, v20, v21
	v_lshl_add_u64 v[28:29], v[34:35], 0, v[120:121]
	v_cvt_pk_bf16_f32 v25, v22, v23
	s_waitcnt lgkmcnt(0)
	v_add_f32_e32 v20, v26, v27
	ds_bpermute_b32 v21, v156, v20
	v_cvt_pk_bf16_f32 v26, v16, v17
	v_lshl_add_u64 v[16:17], v[28:29], 1, s[28:29]
	v_cvt_pk_bf16_f32 v27, v18, v19
	global_store_dwordx4 v[16:17], v[24:27], off sc1
	s_and_saveexec_b64 s[44:45], s[2:3]
	s_cbranch_execz .LBB0_1162
	v_lshl_add_u64 v[16:17], v[32:33], 2, s[14:15]
	s_waitcnt lgkmcnt(0)
	v_add_f32_e32 v18, v20, v21
	global_atomic_add_f32 v[16:17], v18, off
.LBB0_1162:
	s_or_b64 exec, exec, s[44:45]
	v_or_b32_e32 v16, 0xb0, v146
	v_ashrrev_i32_e32 v17, 31, v16
	v_lshlrev_b64 v[18:19], 11, v[16:17]
	v_lshl_add_u64 v[22:23], v[18:19], 0, v[144:145]
	s_waitcnt lgkmcnt(0)
	v_lshl_add_u64 v[20:21], v[22:23], 2, s[12:13]
	global_load_dwordx4 v[24:27], v[20:21], off
	global_load_dwordx4 v[28:31], v[20:21], off offset:16
	s_and_b64 vcc, exec, s[6:7]
	s_waitcnt vmcnt(1)
	v_pk_add_f32 v[14:15], v[14:15], v[26:27]
	v_pk_add_f32 v[12:13], v[12:13], v[24:25]
	s_waitcnt vmcnt(0)
	v_pk_add_f32 v[10:11], v[10:11], v[30:31]
	v_pk_add_f32 v[8:9], v[8:9], v[28:29]
	s_cbranch_vccnz .LBB0_1164
	global_store_dwordx4 v[20:21], v[12:15], off sc1
	global_store_dwordx4 v[20:21], v[8:11], off offset:16 sc1
.LBB0_1164:
	v_lshl_add_u64 v[22:23], v[22:23], 1, s[28:29]
	v_cvt_pk_bf16_f32 v24, v12, v13
	v_cvt_pk_bf16_f32 v25, v14, v15
	v_cvt_pk_bf16_f32 v26, v8, v9
	v_cvt_pk_bf16_f32 v27, v10, v11
	global_store_dwordx4 v[22:23], v[24:27], off sc1
	global_load_dwordx4 v[22:25], v[20:21], off offset:512
	s_nop 0
	global_load_dwordx4 v[26:29], v[20:21], off offset:528
	s_and_b64 vcc, exec, s[6:7]
	s_waitcnt vmcnt(1)
	v_pk_add_f32 v[6:7], v[6:7], v[24:25]
	v_pk_add_f32 v[4:5], v[4:5], v[22:23]
	s_waitcnt vmcnt(0)
	v_pk_add_f32 v[2:3], v[2:3], v[28:29]
	v_pk_add_f32 v[0:1], v[0:1], v[26:27]
	s_cbranch_vccnz .LBB0_1166
	global_store_dwordx4 v[20:21], v[4:7], off offset:512 sc1
	global_store_dwordx4 v[20:21], v[0:3], off offset:528 sc1
.LBB0_1166:
	v_mul_f32_e32 v9, v9, v9
	v_fmac_f32_e32 v9, v8, v8
	v_mul_f32_e32 v8, v11, v11
	v_fmac_f32_e32 v8, v10, v10
	v_add_f32_e32 v8, v9, v8
	v_mul_f32_e32 v9, v5, v5
	v_mul_f32_e32 v10, v7, v7
	v_mul_f32_e32 v13, v13, v13
	v_fmac_f32_e32 v9, v4, v4
	v_fmac_f32_e32 v10, v6, v6
	v_fmac_f32_e32 v13, v12, v12
	v_mul_f32_e32 v12, v15, v15
	v_add_f32_e32 v9, v9, v10
	v_mul_f32_e32 v10, v1, v1
	v_mul_f32_e32 v11, v3, v3
	v_fmac_f32_e32 v12, v14, v14
	v_fmac_f32_e32 v10, v0, v0
	v_fmac_f32_e32 v11, v2, v2
	v_add_f32_e32 v12, v13, v12
	v_add_f32_e32 v10, v10, v11
	v_add_f32_e32 v8, v12, v8
	v_add_f32_e32 v9, v9, v10
	v_add_f32_e32 v10, v8, v9
	ds_bpermute_b32 v11, v155, v10
	v_cvt_pk_bf16_f32 v8, v4, v5
	v_lshl_add_u64 v[12:13], v[18:19], 0, v[120:121]
	v_cvt_pk_bf16_f32 v9, v6, v7
	s_waitcnt lgkmcnt(0)
	v_add_f32_e32 v4, v10, v11
	ds_bpermute_b32 v5, v156, v4
	v_cvt_pk_bf16_f32 v10, v0, v1
	v_lshl_add_u64 v[0:1], v[12:13], 1, s[28:29]
	v_cvt_pk_bf16_f32 v11, v2, v3
	global_store_dwordx4 v[0:1], v[8:11], off sc1
	s_and_saveexec_b64 s[6:7], s[2:3]
	s_cbranch_execz .LBB0_1168
	v_lshl_add_u64 v[0:1], v[16:17], 2, s[14:15]
	s_waitcnt lgkmcnt(0)
	v_add_f32_e32 v2, v4, v5
	global_atomic_add_f32 v[0:1], v2, off

.LBB0_1243:
	v_lshl_or_b32 v148, s36, 8, v151
	v_ashrrev_i32_e32 v149, 31, v148
	v_lshl_add_u64 v[144:145], v[148:149], 2, s[14:15]
	global_load_dword v149, v[144:145], off
	v_or_b32_e32 v160, 16, v148
	v_ashrrev_i32_e32 v161, 31, v160
	v_lshl_add_u64 v[164:165], v[160:161], 2, s[14:15]
	v_lshl_or_b32 v146, s11, 7, v152
	v_mov_b64_e32 v[144:145], s[12:13]
	v_ashrrev_i32_e32 v147, 31, v146
	v_mad_i64_i32 v[158:159], s[38:39], v148, s56, v[144:145]
	v_lshlrev_b64 v[146:147], 1, v[146:147]
	v_lshl_add_u64 v[158:159], v[158:159], 0, v[146:147]
	s_andn2_b64 vcc, exec, s[2:3]
	s_mov_b64 s[2:3], -1
	s_waitcnt vmcnt(0)
	v_fmamk_f32 v149, v149, 0x3a000000, v156
	v_rsq_f32_e32 v162, v149
	s_nop 0
	v_pk_mul_f32 v[122:123], v[122:123], v[162:163] op_sel_hi:[1,0]
	v_pk_mul_f32 v[126:127], v[126:127], v[162:163] op_sel_hi:[1,0]
	v_pk_mul_f32 v[124:125], v[124:125], v[162:163] op_sel_hi:[1,0]
	v_pk_mul_f32 v[120:121], v[120:121], v[162:163] op_sel_hi:[1,0]
	v_mul_f32_e32 v168, 0xbfb8aa3b, v123
	v_pk_mul_f32 v[118:119], v[118:119], v[162:163] op_sel_hi:[1,0]
	v_pk_mul_f32 v[116:117], v[116:117], v[162:163] op_sel_hi:[1,0]
	v_pk_mul_f32 v[114:115], v[114:115], v[162:163] op_sel_hi:[1,0]
	v_pk_mul_f32 v[112:113], v[112:113], v[162:163] op_sel_hi:[1,0]
	v_mul_f32_e32 v149, 0xbfb8aa3b, v124
	v_mul_f32_e32 v157, 0xbfb8aa3b, v125
	v_mul_f32_e32 v161, 0xbfb8aa3b, v126
	v_mul_f32_e32 v162, 0xbfb8aa3b, v127
	v_mul_f32_e32 v163, 0xbfb8aa3b, v120
	v_mul_f32_e32 v166, 0xbfb8aa3b, v121
	v_mul_f32_e32 v167, 0xbfb8aa3b, v122
	v_exp_f32_e32 v168, v168
	v_exp_f32_e32 v149, v149
	v_exp_f32_e32 v157, v157
	v_exp_f32_e32 v161, v161
	v_exp_f32_e32 v162, v162
	v_exp_f32_e32 v163, v163
	v_exp_f32_e32 v166, v166
	v_exp_f32_e32 v167, v167
	v_add_f32_e32 v168, 1.0, v168
	v_add_f32_e32 v149, 1.0, v149
	v_add_f32_e32 v157, 1.0, v157
	v_add_f32_e32 v161, 1.0, v161
	v_add_f32_e32 v162, 1.0, v162
	v_add_f32_e32 v163, 1.0, v163
	v_add_f32_e32 v166, 1.0, v166
	v_add_f32_e32 v167, 1.0, v167
	v_rcp_f32_e32 v168, v168
	v_rcp_f32_e32 v149, v149
	v_rcp_f32_e32 v157, v157
	v_rcp_f32_e32 v161, v161
	v_rcp_f32_e32 v162, v162
	v_rcp_f32_e32 v163, v163
	v_rcp_f32_e32 v166, v166
	v_rcp_f32_e32 v167, v167
	v_mul_f32_e32 v123, v123, v168
	v_mul_f32_e32 v124, v124, v149
	v_mul_f32_e32 v125, v125, v157
	v_mul_f32_e32 v126, v126, v161
	v_mul_f32_e32 v127, v127, v162
	v_mul_f32_e32 v120, v120, v163
	v_mul_f32_e32 v121, v121, v166
	v_mul_f32_e32 v122, v122, v167
	v_mul_f32_e32 v115, v115, v123
	v_mul_f32_e32 v116, v116, v124
	v_mul_f32_e32 v117, v117, v125
	v_mul_f32_e32 v118, v118, v126
	v_mul_f32_e32 v119, v119, v127
	v_mul_f32_e32 v120, v112, v120
	v_mul_f32_e32 v121, v113, v121
	v_mul_f32_e32 v122, v114, v122
	v_cvt_pk_bf16_f32 v112, v116, v117
	v_cvt_pk_bf16_f32 v113, v118, v119
	v_cvt_pk_bf16_f32 v114, v120, v121
	v_cvt_pk_bf16_f32 v115, v122, v115
	global_store_dwordx4 v[158:159], v[112:115], off sc1
	global_load_dword v113, v[164:165], off
	s_nop 0
	v_or_b32_e32 v112, 32, v148
	v_mad_i64_i32 v[114:115], s[38:39], v160, s56, v[144:145]
	v_lshl_add_u64 v[114:115], v[114:115], 0, v[146:147]
	s_waitcnt vmcnt(0)
	v_fmamk_f32 v113, v113, 0x3a000000, v156
	v_rsq_f32_e32 v116, v113
	v_ashrrev_i32_e32 v113, 31, v112
	v_lshl_add_u64 v[118:119], v[112:113], 2, s[14:15]
	v_pk_mul_f32 v[106:107], v[106:107], v[116:117] op_sel_hi:[1,0]
	v_pk_mul_f32 v[110:111], v[110:111], v[116:117] op_sel_hi:[1,0]
	v_pk_mul_f32 v[108:109], v[108:109], v[116:117] op_sel_hi:[1,0]
	v_pk_mul_f32 v[104:105], v[104:105], v[116:117] op_sel_hi:[1,0]
	v_mul_f32_e32 v124, 0xbfb8aa3b, v107
	v_pk_mul_f32 v[102:103], v[102:103], v[116:117] op_sel_hi:[1,0]
	v_pk_mul_f32 v[100:101], v[100:101], v[116:117] op_sel_hi:[1,0]
	v_pk_mul_f32 v[98:99], v[98:99], v[116:117] op_sel_hi:[1,0]
	v_pk_mul_f32 v[96:97], v[96:97], v[116:117] op_sel_hi:[1,0]
	v_mul_f32_e32 v113, 0xbfb8aa3b, v108
	v_mul_f32_e32 v116, 0xbfb8aa3b, v109
	v_mul_f32_e32 v117, 0xbfb8aa3b, v110
	v_mul_f32_e32 v120, 0xbfb8aa3b, v111
	v_mul_f32_e32 v121, 0xbfb8aa3b, v104
	v_mul_f32_e32 v122, 0xbfb8aa3b, v105
	v_mul_f32_e32 v123, 0xbfb8aa3b, v106
	v_exp_f32_e32 v124, v124
	v_exp_f32_e32 v113, v113
	v_exp_f32_e32 v116, v116
	v_exp_f32_e32 v117, v117
	v_exp_f32_e32 v120, v120
	v_exp_f32_e32 v121, v121
	v_exp_f32_e32 v122, v122
	v_exp_f32_e32 v123, v123
	v_add_f32_e32 v124, 1.0, v124
	v_add_f32_e32 v113, 1.0, v113
	v_add_f32_e32 v116, 1.0, v116
	v_add_f32_e32 v117, 1.0, v117
	v_add_f32_e32 v120, 1.0, v120
	v_add_f32_e32 v121, 1.0, v121
	v_add_f32_e32 v122, 1.0, v122
	v_add_f32_e32 v123, 1.0, v123
	v_rcp_f32_e32 v124, v124
	v_rcp_f32_e32 v113, v113
	v_rcp_f32_e32 v116, v116
	v_rcp_f32_e32 v117, v117
	v_rcp_f32_e32 v120, v120
	v_rcp_f32_e32 v121, v121
	v_rcp_f32_e32 v122, v122
	v_rcp_f32_e32 v123, v123
	v_mul_f32_e32 v107, v107, v124
	v_mul_f32_e32 v108, v108, v113
	v_mul_f32_e32 v109, v109, v116
	v_mul_f32_e32 v110, v110, v117
	v_mul_f32_e32 v111, v111, v120
	v_mul_f32_e32 v104, v104, v121
	v_mul_f32_e32 v105, v105, v122
	v_mul_f32_e32 v106, v106, v123
	v_mul_f32_e32 v99, v99, v107
	v_mul_f32_e32 v100, v100, v108
	v_mul_f32_e32 v101, v101, v109
	v_mul_f32_e32 v102, v102, v110
	v_mul_f32_e32 v103, v103, v111
	v_mul_f32_e32 v104, v96, v104
	v_mul_f32_e32 v105, v97, v105
	v_mul_f32_e32 v106, v98, v106
	v_cvt_pk_bf16_f32 v96, v100, v101
	v_cvt_pk_bf16_f32 v97, v102, v103
	v_cvt_pk_bf16_f32 v98, v104, v105
	v_cvt_pk_bf16_f32 v99, v106, v99
	global_store_dwordx4 v[114:115], v[96:99], off sc1
	global_load_dword v97, v[118:119], off
	s_nop 0
	v_or_b32_e32 v96, 48, v148
	v_mad_i64_i32 v[98:99], s[38:39], v112, s56, v[144:145]
	v_lshl_add_u64 v[98:99], v[98:99], 0, v[146:147]
	s_waitcnt vmcnt(0)
	v_fmamk_f32 v97, v97, 0x3a000000, v156
	v_rsq_f32_e32 v100, v97
	v_ashrrev_i32_e32 v97, 31, v96
	v_lshl_add_u64 v[102:103], v[96:97], 2, s[14:15]
	v_pk_mul_f32 v[90:91], v[90:91], v[100:101] op_sel_hi:[1,0]
	v_pk_mul_f32 v[94:95], v[94:95], v[100:101] op_sel_hi:[1,0]
	v_pk_mul_f32 v[92:93], v[92:93], v[100:101] op_sel_hi:[1,0]
	v_pk_mul_f32 v[88:89], v[88:89], v[100:101] op_sel_hi:[1,0]
	v_mul_f32_e32 v108, 0xbfb8aa3b, v91
	v_pk_mul_f32 v[86:87], v[86:87], v[100:101] op_sel_hi:[1,0]
	v_pk_mul_f32 v[84:85], v[84:85], v[100:101] op_sel_hi:[1,0]
	v_pk_mul_f32 v[82:83], v[82:83], v[100:101] op_sel_hi:[1,0]
	v_pk_mul_f32 v[80:81], v[80:81], v[100:101] op_sel_hi:[1,0]
	v_mul_f32_e32 v97, 0xbfb8aa3b, v92
	v_mul_f32_e32 v100, 0xbfb8aa3b, v93
	v_mul_f32_e32 v101, 0xbfb8aa3b, v94
	v_mul_f32_e32 v104, 0xbfb8aa3b, v95
	v_mul_f32_e32 v105, 0xbfb8aa3b, v88
	v_mul_f32_e32 v106, 0xbfb8aa3b, v89
	v_mul_f32_e32 v107, 0xbfb8aa3b, v90
	v_exp_f32_e32 v108, v108
	v_exp_f32_e32 v97, v97
	v_exp_f32_e32 v100, v100
	v_exp_f32_e32 v101, v101
	v_exp_f32_e32 v104, v104
	v_exp_f32_e32 v105, v105
	v_exp_f32_e32 v106, v106
	v_exp_f32_e32 v107, v107
	v_add_f32_e32 v108, 1.0, v108
	v_add_f32_e32 v97, 1.0, v97
	v_add_f32_e32 v100, 1.0, v100
	v_add_f32_e32 v101, 1.0, v101
	v_add_f32_e32 v104, 1.0, v104
	v_add_f32_e32 v105, 1.0, v105
	v_add_f32_e32 v106, 1.0, v106
	v_add_f32_e32 v107, 1.0, v107
	v_rcp_f32_e32 v108, v108
	v_rcp_f32_e32 v97, v97
	v_rcp_f32_e32 v100, v100
	v_rcp_f32_e32 v101, v101
	v_rcp_f32_e32 v104, v104
	v_rcp_f32_e32 v105, v105
	v_rcp_f32_e32 v106, v106
	v_rcp_f32_e32 v107, v107
	v_mul_f32_e32 v91, v91, v108
	v_mul_f32_e32 v92, v92, v97
	v_mul_f32_e32 v93, v93, v100
	v_mul_f32_e32 v94, v94, v101
	v_mul_f32_e32 v95, v95, v104
	v_mul_f32_e32 v88, v88, v105
	v_mul_f32_e32 v89, v89, v106
	v_mul_f32_e32 v90, v90, v107
	v_mul_f32_e32 v83, v83, v91
	v_mul_f32_e32 v84, v84, v92
	v_mul_f32_e32 v85, v85, v93
	v_mul_f32_e32 v86, v86, v94
	v_mul_f32_e32 v87, v87, v95
	v_mul_f32_e32 v88, v80, v88
	v_mul_f32_e32 v89, v81, v89
	v_mul_f32_e32 v90, v82, v90
	v_cvt_pk_bf16_f32 v80, v84, v85
	v_cvt_pk_bf16_f32 v81, v86, v87
	v_cvt_pk_bf16_f32 v82, v88, v89
	v_cvt_pk_bf16_f32 v83, v90, v83
	global_store_dwordx4 v[98:99], v[80:83], off sc1
	global_load_dword v81, v[102:103], off
	s_nop 0
	v_or_b32_e32 v80, 0x80, v148
	v_mad_i64_i32 v[82:83], s[38:39], v96, s56, v[144:145]
	v_lshl_add_u64 v[82:83], v[82:83], 0, v[146:147]
	s_waitcnt vmcnt(0)
	v_fmamk_f32 v81, v81, 0x3a000000, v156
	v_rsq_f32_e32 v84, v81
	v_ashrrev_i32_e32 v81, 31, v80
	v_lshl_add_u64 v[86:87], v[80:81], 2, s[14:15]
	v_pk_mul_f32 v[74:75], v[74:75], v[84:85] op_sel_hi:[1,0]
	v_pk_mul_f32 v[78:79], v[78:79], v[84:85] op_sel_hi:[1,0]
	v_pk_mul_f32 v[76:77], v[76:77], v[84:85] op_sel_hi:[1,0]
	v_pk_mul_f32 v[72:73], v[72:73], v[84:85] op_sel_hi:[1,0]
	v_mul_f32_e32 v92, 0xbfb8aa3b, v75
	v_pk_mul_f32 v[70:71], v[70:71], v[84:85] op_sel_hi:[1,0]
	v_pk_mul_f32 v[68:69], v[68:69], v[84:85] op_sel_hi:[1,0]
	v_pk_mul_f32 v[66:67], v[66:67], v[84:85] op_sel_hi:[1,0]
	v_pk_mul_f32 v[64:65], v[64:65], v[84:85] op_sel_hi:[1,0]
	v_mul_f32_e32 v81, 0xbfb8aa3b, v76
	v_mul_f32_e32 v84, 0xbfb8aa3b, v77
	v_mul_f32_e32 v85, 0xbfb8aa3b, v78
	v_mul_f32_e32 v88, 0xbfb8aa3b, v79
	v_mul_f32_e32 v89, 0xbfb8aa3b, v72
	v_mul_f32_e32 v90, 0xbfb8aa3b, v73
	v_mul_f32_e32 v91, 0xbfb8aa3b, v74
	v_exp_f32_e32 v92, v92
	v_exp_f32_e32 v81, v81
	v_exp_f32_e32 v84, v84
	v_exp_f32_e32 v85, v85
	v_exp_f32_e32 v88, v88
	v_exp_f32_e32 v89, v89
	v_exp_f32_e32 v90, v90
	v_exp_f32_e32 v91, v91
	v_add_f32_e32 v92, 1.0, v92
	v_add_f32_e32 v81, 1.0, v81
	v_add_f32_e32 v84, 1.0, v84
	v_add_f32_e32 v85, 1.0, v85
	v_add_f32_e32 v88, 1.0, v88
	v_add_f32_e32 v89, 1.0, v89
	v_add_f32_e32 v90, 1.0, v90
	v_add_f32_e32 v91, 1.0, v91
	v_rcp_f32_e32 v92, v92
	v_rcp_f32_e32 v81, v81
	v_rcp_f32_e32 v84, v84
	v_rcp_f32_e32 v85, v85
	v_rcp_f32_e32 v88, v88
	v_rcp_f32_e32 v89, v89
	v_rcp_f32_e32 v90, v90
	v_rcp_f32_e32 v91, v91
	v_mul_f32_e32 v75, v75, v92
	v_mul_f32_e32 v76, v76, v81
	v_mul_f32_e32 v77, v77, v84
	v_mul_f32_e32 v78, v78, v85
	v_mul_f32_e32 v79, v79, v88
	v_mul_f32_e32 v72, v72, v89
	v_mul_f32_e32 v73, v73, v90
	v_mul_f32_e32 v74, v74, v91
	v_mul_f32_e32 v67, v67, v75
	v_mul_f32_e32 v68, v68, v76
	v_mul_f32_e32 v69, v69, v77
	v_mul_f32_e32 v70, v70, v78
	v_mul_f32_e32 v71, v71, v79
	v_mul_f32_e32 v72, v64, v72
	v_mul_f32_e32 v73, v65, v73
	v_mul_f32_e32 v74, v66, v74
	v_cvt_pk_bf16_f32 v64, v68, v69
	v_cvt_pk_bf16_f32 v65, v70, v71
	v_cvt_pk_bf16_f32 v66, v72, v73
	v_cvt_pk_bf16_f32 v67, v74, v67
	global_store_dwordx4 v[82:83], v[64:67], off sc1
	global_load_dword v65, v[86:87], off
	s_nop 0
	v_or_b32_e32 v64, 0x90, v148
	v_mad_i64_i32 v[66:67], s[38:39], v80, s56, v[144:145]
	v_lshl_add_u64 v[66:67], v[66:67], 0, v[146:147]
	s_waitcnt vmcnt(0)
	v_fmamk_f32 v65, v65, 0x3a000000, v156
	v_rsq_f32_e32 v68, v65
	v_ashrrev_i32_e32 v65, 31, v64
	v_lshl_add_u64 v[70:71], v[64:65], 2, s[14:15]
	v_pk_mul_f32 v[58:59], v[58:59], v[68:69] op_sel_hi:[1,0]
	v_pk_mul_f32 v[62:63], v[62:63], v[68:69] op_sel_hi:[1,0]
	v_pk_mul_f32 v[60:61], v[60:61], v[68:69] op_sel_hi:[1,0]
	v_pk_mul_f32 v[56:57], v[56:57], v[68:69] op_sel_hi:[1,0]
	v_mul_f32_e32 v76, 0xbfb8aa3b, v59
	v_pk_mul_f32 v[54:55], v[54:55], v[68:69] op_sel_hi:[1,0]
	v_pk_mul_f32 v[52:53], v[52:53], v[68:69] op_sel_hi:[1,0]
	v_pk_mul_f32 v[50:51], v[50:51], v[68:69] op_sel_hi:[1,0]
	v_pk_mul_f32 v[48:49], v[48:49], v[68:69] op_sel_hi:[1,0]
	v_mul_f32_e32 v65, 0xbfb8aa3b, v60
	v_mul_f32_e32 v68, 0xbfb8aa3b, v61
	v_mul_f32_e32 v69, 0xbfb8aa3b, v62
	v_mul_f32_e32 v72, 0xbfb8aa3b, v63
	v_mul_f32_e32 v73, 0xbfb8aa3b, v56
	v_mul_f32_e32 v74, 0xbfb8aa3b, v57
	v_mul_f32_e32 v75, 0xbfb8aa3b, v58
	v_exp_f32_e32 v76, v76
	v_exp_f32_e32 v65, v65
	v_exp_f32_e32 v68, v68
	v_exp_f32_e32 v69, v69
	v_exp_f32_e32 v72, v72
	v_exp_f32_e32 v73, v73
	v_exp_f32_e32 v74, v74
	v_exp_f32_e32 v75, v75
	v_add_f32_e32 v76, 1.0, v76
	v_add_f32_e32 v65, 1.0, v65
	v_add_f32_e32 v68, 1.0, v68
	v_add_f32_e32 v69, 1.0, v69
	v_add_f32_e32 v72, 1.0, v72
	v_add_f32_e32 v73, 1.0, v73
	v_add_f32_e32 v74, 1.0, v74
	v_add_f32_e32 v75, 1.0, v75
	v_rcp_f32_e32 v76, v76
	v_rcp_f32_e32 v65, v65
	v_rcp_f32_e32 v68, v68
	v_rcp_f32_e32 v69, v69
	v_rcp_f32_e32 v72, v72
	v_rcp_f32_e32 v73, v73
	v_rcp_f32_e32 v74, v74
	v_rcp_f32_e32 v75, v75
	v_mul_f32_e32 v59, v59, v76
	v_mul_f32_e32 v60, v60, v65
	v_mul_f32_e32 v61, v61, v68
	v_mul_f32_e32 v62, v62, v69
	v_mul_f32_e32 v63, v63, v72
	v_mul_f32_e32 v56, v56, v73
	v_mul_f32_e32 v57, v57, v74
	v_mul_f32_e32 v58, v58, v75
	v_mul_f32_e32 v51, v51, v59
	v_mul_f32_e32 v52, v52, v60
	v_mul_f32_e32 v53, v53, v61
	v_mul_f32_e32 v54, v54, v62
	v_mul_f32_e32 v55, v55, v63
	v_mul_f32_e32 v56, v48, v56
	v_mul_f32_e32 v57, v49, v57
	v_mul_f32_e32 v58, v50, v58
	v_cvt_pk_bf16_f32 v48, v52, v53
	v_cvt_pk_bf16_f32 v49, v54, v55
	v_cvt_pk_bf16_f32 v50, v56, v57
	v_cvt_pk_bf16_f32 v51, v58, v51
	global_store_dwordx4 v[66:67], v[48:51], off sc1
	global_load_dword v49, v[70:71], off
	s_nop 0
	v_or_b32_e32 v48, 0xa0, v148
	v_mad_i64_i32 v[50:51], s[38:39], v64, s56, v[144:145]
	v_lshl_add_u64 v[50:51], v[50:51], 0, v[146:147]
	s_waitcnt vmcnt(0)
	v_fmamk_f32 v49, v49, 0x3a000000, v156
	v_rsq_f32_e32 v52, v49
	v_ashrrev_i32_e32 v49, 31, v48
	v_lshl_add_u64 v[54:55], v[48:49], 2, s[14:15]
	v_pk_mul_f32 v[42:43], v[42:43], v[52:53] op_sel_hi:[1,0]
	v_pk_mul_f32 v[46:47], v[46:47], v[52:53] op_sel_hi:[1,0]
	v_pk_mul_f32 v[44:45], v[44:45], v[52:53] op_sel_hi:[1,0]
	v_pk_mul_f32 v[40:41], v[40:41], v[52:53] op_sel_hi:[1,0]
	v_mul_f32_e32 v60, 0xbfb8aa3b, v43
	v_pk_mul_f32 v[38:39], v[38:39], v[52:53] op_sel_hi:[1,0]
	v_pk_mul_f32 v[36:37], v[36:37], v[52:53] op_sel_hi:[1,0]
	v_pk_mul_f32 v[34:35], v[34:35], v[52:53] op_sel_hi:[1,0]
	v_pk_mul_f32 v[32:33], v[32:33], v[52:53] op_sel_hi:[1,0]
	v_mul_f32_e32 v49, 0xbfb8aa3b, v44
	v_mul_f32_e32 v52, 0xbfb8aa3b, v45
	v_mul_f32_e32 v53, 0xbfb8aa3b, v46
	v_mul_f32_e32 v56, 0xbfb8aa3b, v47
	v_mul_f32_e32 v57, 0xbfb8aa3b, v40
	v_mul_f32_e32 v58, 0xbfb8aa3b, v41
	v_mul_f32_e32 v59, 0xbfb8aa3b, v42
	v_exp_f32_e32 v60, v60
	v_exp_f32_e32 v49, v49
	v_exp_f32_e32 v52, v52
	v_exp_f32_e32 v53, v53
	v_exp_f32_e32 v56, v56
	v_exp_f32_e32 v57, v57
	v_exp_f32_e32 v58, v58
	v_exp_f32_e32 v59, v59
	v_add_f32_e32 v60, 1.0, v60
	v_add_f32_e32 v49, 1.0, v49
	v_add_f32_e32 v52, 1.0, v52
	v_add_f32_e32 v53, 1.0, v53
	v_add_f32_e32 v56, 1.0, v56
	v_add_f32_e32 v57, 1.0, v57
	v_add_f32_e32 v58, 1.0, v58
	v_add_f32_e32 v59, 1.0, v59
	v_rcp_f32_e32 v60, v60
	v_rcp_f32_e32 v49, v49
	v_rcp_f32_e32 v52, v52
	v_rcp_f32_e32 v53, v53
	v_rcp_f32_e32 v56, v56
	v_rcp_f32_e32 v57, v57
	v_rcp_f32_e32 v58, v58
	v_rcp_f32_e32 v59, v59
	v_mul_f32_e32 v43, v43, v60
	v_mul_f32_e32 v44, v44, v49
	v_mul_f32_e32 v45, v45, v52
	v_mul_f32_e32 v46, v46, v53
	v_mul_f32_e32 v47, v47, v56
	v_mul_f32_e32 v40, v40, v57
	v_mul_f32_e32 v41, v41, v58
	v_mul_f32_e32 v42, v42, v59
	v_mul_f32_e32 v35, v35, v43
	v_mul_f32_e32 v36, v36, v44
	v_mul_f32_e32 v37, v37, v45
	v_mul_f32_e32 v38, v38, v46
	v_mul_f32_e32 v39, v39, v47
	v_mul_f32_e32 v40, v32, v40
	v_mul_f32_e32 v41, v33, v41
	v_mul_f32_e32 v42, v34, v42
	v_cvt_pk_bf16_f32 v32, v36, v37
	v_cvt_pk_bf16_f32 v33, v38, v39
	v_cvt_pk_bf16_f32 v34, v40, v41
	v_cvt_pk_bf16_f32 v35, v42, v35
	global_store_dwordx4 v[50:51], v[32:35], off sc1
	global_load_dword v33, v[54:55], off
	s_nop 0
	v_or_b32_e32 v32, 0xb0, v148
	v_mad_i64_i32 v[34:35], s[38:39], v48, s56, v[144:145]
	v_lshl_add_u64 v[34:35], v[34:35], 0, v[146:147]
	s_waitcnt vmcnt(0)
	v_fmamk_f32 v33, v33, 0x3a000000, v156
	v_rsq_f32_e32 v36, v33
	v_ashrrev_i32_e32 v33, 31, v32
	v_lshl_add_u64 v[38:39], v[32:33], 2, s[14:15]
	v_pk_mul_f32 v[26:27], v[26:27], v[36:37] op_sel_hi:[1,0]
	v_pk_mul_f32 v[30:31], v[30:31], v[36:37] op_sel_hi:[1,0]
	v_pk_mul_f32 v[28:29], v[28:29], v[36:37] op_sel_hi:[1,0]
	v_pk_mul_f32 v[24:25], v[24:25], v[36:37] op_sel_hi:[1,0]
	v_mul_f32_e32 v44, 0xbfb8aa3b, v27
	v_pk_mul_f32 v[22:23], v[22:23], v[36:37] op_sel_hi:[1,0]
	v_pk_mul_f32 v[20:21], v[20:21], v[36:37] op_sel_hi:[1,0]
	v_pk_mul_f32 v[18:19], v[18:19], v[36:37] op_sel_hi:[1,0]
	v_pk_mul_f32 v[16:17], v[16:17], v[36:37] op_sel_hi:[1,0]
	v_mul_f32_e32 v33, 0xbfb8aa3b, v28
	v_mul_f32_e32 v36, 0xbfb8aa3b, v29
	v_mul_f32_e32 v37, 0xbfb8aa3b, v30
	v_mul_f32_e32 v40, 0xbfb8aa3b, v31
	v_mul_f32_e32 v41, 0xbfb8aa3b, v24
	v_mul_f32_e32 v42, 0xbfb8aa3b, v25
	v_mul_f32_e32 v43, 0xbfb8aa3b, v26
	v_exp_f32_e32 v44, v44
	v_exp_f32_e32 v33, v33
	v_exp_f32_e32 v36, v36
	v_exp_f32_e32 v37, v37
	v_exp_f32_e32 v40, v40
	v_exp_f32_e32 v41, v41
	v_exp_f32_e32 v42, v42
	v_exp_f32_e32 v43, v43
	v_add_f32_e32 v44, 1.0, v44
	v_add_f32_e32 v33, 1.0, v33
	v_add_f32_e32 v36, 1.0, v36
	v_add_f32_e32 v37, 1.0, v37
	v_add_f32_e32 v40, 1.0, v40
	v_add_f32_e32 v41, 1.0, v41
	v_add_f32_e32 v42, 1.0, v42
	v_add_f32_e32 v43, 1.0, v43
	v_rcp_f32_e32 v44, v44
	v_rcp_f32_e32 v33, v33
	v_rcp_f32_e32 v36, v36
	v_rcp_f32_e32 v37, v37
	v_rcp_f32_e32 v40, v40
	v_rcp_f32_e32 v41, v41
	v_rcp_f32_e32 v42, v42
	v_rcp_f32_e32 v43, v43
	v_mul_f32_e32 v27, v27, v44
	v_mul_f32_e32 v28, v28, v33
	v_mul_f32_e32 v29, v29, v36
	v_mul_f32_e32 v30, v30, v37
	v_mul_f32_e32 v31, v31, v40
	v_mul_f32_e32 v24, v24, v41
	v_mul_f32_e32 v25, v25, v42
	v_mul_f32_e32 v26, v26, v43
	v_mul_f32_e32 v19, v19, v27
	v_mul_f32_e32 v20, v20, v28
	v_mul_f32_e32 v21, v21, v29
	v_mul_f32_e32 v22, v22, v30
	v_mul_f32_e32 v23, v23, v31
	v_mul_f32_e32 v24, v16, v24
	v_mul_f32_e32 v25, v17, v25
	v_mul_f32_e32 v26, v18, v26
	v_cvt_pk_bf16_f32 v16, v20, v21
	v_cvt_pk_bf16_f32 v17, v22, v23
	v_cvt_pk_bf16_f32 v18, v24, v25
	v_cvt_pk_bf16_f32 v19, v26, v19
	global_store_dwordx4 v[34:35], v[16:19], off sc1
	global_load_dword v16, v[38:39], off
	s_nop 0
	v_mad_i64_i32 v[18:19], s[38:39], v32, s56, v[144:145]
	v_lshl_add_u64 v[18:19], v[18:19], 0, v[146:147]
	s_waitcnt vmcnt(0)
	v_fmamk_f32 v16, v16, 0x3a000000, v156
	v_rsq_f32_e32 v16, v16
	s_nop 0
	v_pk_mul_f32 v[10:11], v[10:11], v[16:17] op_sel_hi:[1,0]
	v_pk_mul_f32 v[14:15], v[14:15], v[16:17] op_sel_hi:[1,0]
	v_pk_mul_f32 v[12:13], v[12:13], v[16:17] op_sel_hi:[1,0]
	v_pk_mul_f32 v[8:9], v[8:9], v[16:17] op_sel_hi:[1,0]
	v_mul_f32_e32 v25, 0xbfb8aa3b, v11
	v_pk_mul_f32 v[6:7], v[6:7], v[16:17] op_sel_hi:[1,0]
	v_pk_mul_f32 v[4:5], v[4:5], v[16:17] op_sel_hi:[1,0]
	v_pk_mul_f32 v[2:3], v[2:3], v[16:17] op_sel_hi:[1,0]
	v_pk_mul_f32 v[0:1], v[0:1], v[16:17] op_sel_hi:[1,0]
	v_mul_f32_e32 v16, 0xbfb8aa3b, v12
	v_mul_f32_e32 v17, 0xbfb8aa3b, v13
	v_mul_f32_e32 v20, 0xbfb8aa3b, v14
	v_mul_f32_e32 v21, 0xbfb8aa3b, v15
	v_mul_f32_e32 v22, 0xbfb8aa3b, v8
	v_mul_f32_e32 v23, 0xbfb8aa3b, v9
	v_mul_f32_e32 v24, 0xbfb8aa3b, v10
	v_exp_f32_e32 v25, v25
	v_exp_f32_e32 v16, v16
	v_exp_f32_e32 v17, v17
	v_exp_f32_e32 v20, v20
	v_exp_f32_e32 v21, v21
	v_exp_f32_e32 v22, v22
	v_exp_f32_e32 v23, v23
	v_exp_f32_e32 v24, v24
	v_add_f32_e32 v25, 1.0, v25
	v_add_f32_e32 v16, 1.0, v16
	v_add_f32_e32 v17, 1.0, v17
	v_add_f32_e32 v20, 1.0, v20
	v_add_f32_e32 v21, 1.0, v21
	v_add_f32_e32 v22, 1.0, v22
	v_add_f32_e32 v23, 1.0, v23
	v_add_f32_e32 v24, 1.0, v24
	v_rcp_f32_e32 v25, v25
	v_rcp_f32_e32 v16, v16
	v_rcp_f32_e32 v17, v17
	v_rcp_f32_e32 v20, v20
	v_rcp_f32_e32 v21, v21
	v_rcp_f32_e32 v22, v22
	v_rcp_f32_e32 v23, v23
	v_rcp_f32_e32 v24, v24
	v_mul_f32_e32 v11, v11, v25
	v_mul_f32_e32 v12, v12, v16
	v_mul_f32_e32 v13, v13, v17
	v_mul_f32_e32 v14, v14, v20
	v_mul_f32_e32 v15, v15, v21
	v_mul_f32_e32 v8, v8, v22
	v_mul_f32_e32 v9, v9, v23
	v_mul_f32_e32 v10, v10, v24
	v_mul_f32_e32 v3, v3, v11
	v_mul_f32_e32 v4, v4, v12
	v_mul_f32_e32 v5, v5, v13
	v_mul_f32_e32 v6, v6, v14
	v_mul_f32_e32 v7, v7, v15
	v_mul_f32_e32 v8, v0, v8
	v_mul_f32_e32 v9, v1, v9
	v_mul_f32_e32 v10, v2, v10
	v_cvt_pk_bf16_f32 v0, v4, v5
	v_cvt_pk_bf16_f32 v1, v6, v7
	v_cvt_pk_bf16_f32 v2, v8, v9
	v_cvt_pk_bf16_f32 v3, v10, v3
	global_store_dwordx4 v[18:19], v[0:3], off sc1
	s_cbranch_vccnz .LBB0_1236
	s_andn2_b64 vcc, exec, s[8:9]
	s_cbranch_vccnz .LBB0_1235
	s_barrier
	s_branch .LBB0_1235

.LBB0_1330:
	s_andn2_b64 vcc, exec, s[18:19]
	s_cbranch_vccnz .LBB0_1332
	v_lshl_or_b32 v146, s11, 8, v149
	v_ashrrev_i32_e32 v147, 31, v146
	v_lshl_or_b32 v144, s52, 8, v150
	v_ashrrev_i32_e32 v145, 31, v144
	v_lshlrev_b64 v[154:155], 13, v[146:147]
	v_lshl_add_u64 v[154:155], s[12:13], 0, v[154:155]
	v_lshlrev_b64 v[144:145], 2, v[144:145]
	v_lshl_add_u64 v[162:163], v[154:155], 0, v[144:145]
	global_load_dwordx4 v[154:157], v[162:163], off
	global_load_dwordx4 v[158:161], v[162:163], off offset:16
	s_waitcnt vmcnt(0)
	v_pk_fma_f32 v[126:127], v[126:127], 0.5, v[156:157] op_sel_hi:[1,0,1]
	v_pk_fma_f32 v[124:125], v[124:125], 0.5, v[154:155] op_sel_hi:[1,0,1]
	v_pk_fma_f32 v[122:123], v[122:123], 0.5, v[160:161] op_sel_hi:[1,0,1]
	v_pk_fma_f32 v[120:121], v[120:121], 0.5, v[158:159] op_sel_hi:[1,0,1]
	global_store_dwordx4 v[162:163], v[124:127], off sc1
	global_store_dwordx4 v[162:163], v[120:123], off offset:16 sc1
	global_load_dwordx4 v[120:123], v[162:163], off offset:512
	s_nop 0
	global_load_dwordx4 v[124:127], v[162:163], off offset:528
	s_waitcnt vmcnt(1)
	v_pk_fma_f32 v[118:119], v[118:119], 0.5, v[122:123] op_sel_hi:[1,0,1]
	s_waitcnt vmcnt(0)
	v_pk_fma_f32 v[112:113], v[112:113], 0.5, v[124:125] op_sel_hi:[1,0,1]
	v_pk_fma_f32 v[116:117], v[116:117], 0.5, v[120:121] op_sel_hi:[1,0,1]
	v_pk_fma_f32 v[114:115], v[114:115], 0.5, v[126:127] op_sel_hi:[1,0,1]
	global_store_dwordx4 v[162:163], v[116:119], off offset:512 sc1
	global_store_dwordx4 v[162:163], v[112:115], off offset:528 sc1
	s_nop 1
	v_or_b32_e32 v112, 16, v146
	v_ashrrev_i32_e32 v113, 31, v112
	v_lshlrev_b64 v[112:113], 13, v[112:113]
	v_lshl_add_u64 v[112:113], s[12:13], 0, v[112:113]
	v_lshl_add_u64 v[120:121], v[112:113], 0, v[144:145]
	global_load_dwordx4 v[112:115], v[120:121], off
	global_load_dwordx4 v[116:119], v[120:121], off offset:16
	s_waitcnt vmcnt(1)
	v_pk_fma_f32 v[110:111], v[110:111], 0.5, v[114:115] op_sel_hi:[1,0,1]
	v_pk_fma_f32 v[108:109], v[108:109], 0.5, v[112:113] op_sel_hi:[1,0,1]
	s_waitcnt vmcnt(0)
	v_pk_fma_f32 v[106:107], v[106:107], 0.5, v[118:119] op_sel_hi:[1,0,1]
	v_pk_fma_f32 v[104:105], v[104:105], 0.5, v[116:117] op_sel_hi:[1,0,1]
	global_store_dwordx4 v[120:121], v[108:111], off sc1
	global_store_dwordx4 v[120:121], v[104:107], off offset:16 sc1
	global_load_dwordx4 v[104:107], v[120:121], off offset:512
	s_nop 0
	global_load_dwordx4 v[108:111], v[120:121], off offset:528
	s_waitcnt vmcnt(1)
	v_pk_fma_f32 v[102:103], v[102:103], 0.5, v[106:107] op_sel_hi:[1,0,1]
	s_waitcnt vmcnt(0)
	v_pk_fma_f32 v[96:97], v[96:97], 0.5, v[108:109] op_sel_hi:[1,0,1]
	v_pk_fma_f32 v[100:101], v[100:101], 0.5, v[104:105] op_sel_hi:[1,0,1]
	v_pk_fma_f32 v[98:99], v[98:99], 0.5, v[110:111] op_sel_hi:[1,0,1]
	global_store_dwordx4 v[120:121], v[100:103], off offset:512 sc1
	global_store_dwordx4 v[120:121], v[96:99], off offset:528 sc1
	s_nop 1
	v_or_b32_e32 v96, 32, v146
	v_ashrrev_i32_e32 v97, 31, v96
	v_lshlrev_b64 v[96:97], 13, v[96:97]
	v_lshl_add_u64 v[96:97], s[12:13], 0, v[96:97]
	v_lshl_add_u64 v[104:105], v[96:97], 0, v[144:145]
	global_load_dwordx4 v[96:99], v[104:105], off
	global_load_dwordx4 v[100:103], v[104:105], off offset:16
	s_waitcnt vmcnt(1)
	v_pk_fma_f32 v[94:95], v[94:95], 0.5, v[98:99] op_sel_hi:[1,0,1]
	v_pk_fma_f32 v[92:93], v[92:93], 0.5, v[96:97] op_sel_hi:[1,0,1]
	s_waitcnt vmcnt(0)
	v_pk_fma_f32 v[90:91], v[90:91], 0.5, v[102:103] op_sel_hi:[1,0,1]
	v_pk_fma_f32 v[88:89], v[88:89], 0.5, v[100:101] op_sel_hi:[1,0,1]
	global_store_dwordx4 v[104:105], v[92:95], off sc1
	global_store_dwordx4 v[104:105], v[88:91], off offset:16 sc1
	global_load_dwordx4 v[88:91], v[104:105], off offset:512
	s_nop 0
	global_load_dwordx4 v[92:95], v[104:105], off offset:528
	s_waitcnt vmcnt(1)
	v_pk_fma_f32 v[86:87], v[86:87], 0.5, v[90:91] op_sel_hi:[1,0,1]
	s_waitcnt vmcnt(0)
	v_pk_fma_f32 v[80:81], v[80:81], 0.5, v[92:93] op_sel_hi:[1,0,1]
	v_pk_fma_f32 v[84:85], v[84:85], 0.5, v[88:89] op_sel_hi:[1,0,1]
	v_pk_fma_f32 v[82:83], v[82:83], 0.5, v[94:95] op_sel_hi:[1,0,1]
	global_store_dwordx4 v[104:105], v[84:87], off offset:512 sc1
	global_store_dwordx4 v[104:105], v[80:83], off offset:528 sc1
	s_nop 1
	v_or_b32_e32 v80, 48, v146
	v_ashrrev_i32_e32 v81, 31, v80
	v_lshlrev_b64 v[80:81], 13, v[80:81]
	v_lshl_add_u64 v[80:81], s[12:13], 0, v[80:81]
	v_lshl_add_u64 v[88:89], v[80:81], 0, v[144:145]
	global_load_dwordx4 v[80:83], v[88:89], off
	global_load_dwordx4 v[84:87], v[88:89], off offset:16
	s_waitcnt vmcnt(1)
	v_pk_fma_f32 v[78:79], v[78:79], 0.5, v[82:83] op_sel_hi:[1,0,1]
	v_pk_fma_f32 v[76:77], v[76:77], 0.5, v[80:81] op_sel_hi:[1,0,1]
	s_waitcnt vmcnt(0)
	v_pk_fma_f32 v[74:75], v[74:75], 0.5, v[86:87] op_sel_hi:[1,0,1]
	v_pk_fma_f32 v[72:73], v[72:73], 0.5, v[84:85] op_sel_hi:[1,0,1]
	global_store_dwordx4 v[88:89], v[76:79], off sc1
	global_store_dwordx4 v[88:89], v[72:75], off offset:16 sc1
	global_load_dwordx4 v[72:75], v[88:89], off offset:512
	s_nop 0
	global_load_dwordx4 v[76:79], v[88:89], off offset:528
	s_waitcnt vmcnt(1)
	v_pk_fma_f32 v[70:71], v[70:71], 0.5, v[74:75] op_sel_hi:[1,0,1]
	s_waitcnt vmcnt(0)
	v_pk_fma_f32 v[64:65], v[64:65], 0.5, v[76:77] op_sel_hi:[1,0,1]
	v_pk_fma_f32 v[68:69], v[68:69], 0.5, v[72:73] op_sel_hi:[1,0,1]
	v_pk_fma_f32 v[66:67], v[66:67], 0.5, v[78:79] op_sel_hi:[1,0,1]
	global_store_dwordx4 v[88:89], v[68:71], off offset:512 sc1
	global_store_dwordx4 v[88:89], v[64:67], off offset:528 sc1
	s_nop 1
	v_or_b32_e32 v64, 0x80, v146
	v_ashrrev_i32_e32 v65, 31, v64
	v_lshlrev_b64 v[64:65], 13, v[64:65]
	v_lshl_add_u64 v[64:65], s[12:13], 0, v[64:65]
	v_lshl_add_u64 v[72:73], v[64:65], 0, v[144:145]
	global_load_dwordx4 v[64:67], v[72:73], off
	global_load_dwordx4 v[68:71], v[72:73], off offset:16
	s_waitcnt vmcnt(1)
	v_pk_fma_f32 v[62:63], v[62:63], 0.5, v[66:67] op_sel_hi:[1,0,1]
	v_pk_fma_f32 v[60:61], v[60:61], 0.5, v[64:65] op_sel_hi:[1,0,1]
	s_waitcnt vmcnt(0)
	v_pk_fma_f32 v[58:59], v[58:59], 0.5, v[70:71] op_sel_hi:[1,0,1]
	v_pk_fma_f32 v[56:57], v[56:57], 0.5, v[68:69] op_sel_hi:[1,0,1]
	global_store_dwordx4 v[72:73], v[60:63], off sc1
	global_store_dwordx4 v[72:73], v[56:59], off offset:16 sc1
	global_load_dwordx4 v[56:59], v[72:73], off offset:512
	s_nop 0
	global_load_dwordx4 v[60:63], v[72:73], off offset:528
	s_waitcnt vmcnt(1)
	v_pk_fma_f32 v[54:55], v[54:55], 0.5, v[58:59] op_sel_hi:[1,0,1]
	s_waitcnt vmcnt(0)
	v_pk_fma_f32 v[48:49], v[48:49], 0.5, v[60:61] op_sel_hi:[1,0,1]
	v_pk_fma_f32 v[52:53], v[52:53], 0.5, v[56:57] op_sel_hi:[1,0,1]
	v_pk_fma_f32 v[50:51], v[50:51], 0.5, v[62:63] op_sel_hi:[1,0,1]
	global_store_dwordx4 v[72:73], v[52:55], off offset:512 sc1
	global_store_dwordx4 v[72:73], v[48:51], off offset:528 sc1
	s_nop 1
	v_or_b32_e32 v48, 0x90, v146
	v_ashrrev_i32_e32 v49, 31, v48
	v_lshlrev_b64 v[48:49], 13, v[48:49]
	v_lshl_add_u64 v[48:49], s[12:13], 0, v[48:49]
	v_lshl_add_u64 v[56:57], v[48:49], 0, v[144:145]
	global_load_dwordx4 v[48:51], v[56:57], off
	global_load_dwordx4 v[52:55], v[56:57], off offset:16
	s_waitcnt vmcnt(1)
	v_pk_fma_f32 v[46:47], v[46:47], 0.5, v[50:51] op_sel_hi:[1,0,1]
	v_pk_fma_f32 v[44:45], v[44:45], 0.5, v[48:49] op_sel_hi:[1,0,1]
	s_waitcnt vmcnt(0)
	v_pk_fma_f32 v[42:43], v[42:43], 0.5, v[54:55] op_sel_hi:[1,0,1]
	v_pk_fma_f32 v[40:41], v[40:41], 0.5, v[52:53] op_sel_hi:[1,0,1]
	global_store_dwordx4 v[56:57], v[44:47], off sc1
	global_store_dwordx4 v[56:57], v[40:43], off offset:16 sc1
	global_load_dwordx4 v[40:43], v[56:57], off offset:512
	s_nop 0
	global_load_dwordx4 v[44:47], v[56:57], off offset:528
	s_waitcnt vmcnt(1)
	v_pk_fma_f32 v[38:39], v[38:39], 0.5, v[42:43] op_sel_hi:[1,0,1]
	s_waitcnt vmcnt(0)
	v_pk_fma_f32 v[32:33], v[32:33], 0.5, v[44:45] op_sel_hi:[1,0,1]
	v_pk_fma_f32 v[36:37], v[36:37], 0.5, v[40:41] op_sel_hi:[1,0,1]
	v_pk_fma_f32 v[34:35], v[34:35], 0.5, v[46:47] op_sel_hi:[1,0,1]
	global_store_dwordx4 v[56:57], v[36:39], off offset:512 sc1
	global_store_dwordx4 v[56:57], v[32:35], off offset:528 sc1
	s_nop 1
	v_or_b32_e32 v32, 0xa0, v146
	v_ashrrev_i32_e32 v33, 31, v32
	v_lshlrev_b64 v[32:33], 13, v[32:33]
	v_lshl_add_u64 v[32:33], s[12:13], 0, v[32:33]
	v_lshl_add_u64 v[40:41], v[32:33], 0, v[144:145]
	global_load_dwordx4 v[32:35], v[40:41], off
	global_load_dwordx4 v[36:39], v[40:41], off offset:16
	s_waitcnt vmcnt(1)
	v_pk_fma_f32 v[30:31], v[30:31], 0.5, v[34:35] op_sel_hi:[1,0,1]
	v_pk_fma_f32 v[28:29], v[28:29], 0.5, v[32:33] op_sel_hi:[1,0,1]
	s_waitcnt vmcnt(0)
	v_pk_fma_f32 v[26:27], v[26:27], 0.5, v[38:39] op_sel_hi:[1,0,1]
	v_pk_fma_f32 v[24:25], v[24:25], 0.5, v[36:37] op_sel_hi:[1,0,1]
	global_store_dwordx4 v[40:41], v[28:31], off sc1
	global_store_dwordx4 v[40:41], v[24:27], off offset:16 sc1
	global_load_dwordx4 v[24:27], v[40:41], off offset:512
	s_nop 0
	global_load_dwordx4 v[28:31], v[40:41], off offset:528
	s_waitcnt vmcnt(1)
	v_pk_fma_f32 v[22:23], v[22:23], 0.5, v[26:27] op_sel_hi:[1,0,1]
	s_waitcnt vmcnt(0)
	v_pk_fma_f32 v[16:17], v[16:17], 0.5, v[28:29] op_sel_hi:[1,0,1]
	v_pk_fma_f32 v[20:21], v[20:21], 0.5, v[24:25] op_sel_hi:[1,0,1]
	v_pk_fma_f32 v[18:19], v[18:19], 0.5, v[30:31] op_sel_hi:[1,0,1]
	global_store_dwordx4 v[40:41], v[20:23], off offset:512 sc1
	global_store_dwordx4 v[40:41], v[16:19], off offset:528 sc1
	s_nop 1
	v_or_b32_e32 v16, 0xb0, v146
	v_ashrrev_i32_e32 v17, 31, v16
	v_lshlrev_b64 v[16:17], 13, v[16:17]
	v_lshl_add_u64 v[16:17], s[12:13], 0, v[16:17]
	v_lshl_add_u64 v[16:17], v[16:17], 0, v[144:145]
	global_load_dwordx4 v[18:21], v[16:17], off
	global_load_dwordx4 v[22:25], v[16:17], off offset:16
	s_waitcnt vmcnt(1)
	v_pk_fma_f32 v[14:15], v[14:15], 0.5, v[20:21] op_sel_hi:[1,0,1]
	v_pk_fma_f32 v[12:13], v[12:13], 0.5, v[18:19] op_sel_hi:[1,0,1]
	s_waitcnt vmcnt(0)
	v_pk_fma_f32 v[10:11], v[10:11], 0.5, v[24:25] op_sel_hi:[1,0,1]
	v_pk_fma_f32 v[8:9], v[8:9], 0.5, v[22:23] op_sel_hi:[1,0,1]
	global_store_dwordx4 v[16:17], v[12:15], off sc1
	global_store_dwordx4 v[16:17], v[8:11], off offset:16 sc1
	global_load_dwordx4 v[8:11], v[16:17], off offset:512
	s_nop 0
	global_load_dwordx4 v[12:15], v[16:17], off offset:528
	s_waitcnt vmcnt(1)
	v_pk_fma_f32 v[6:7], v[6:7], 0.5, v[10:11] op_sel_hi:[1,0,1]
	v_pk_fma_f32 v[4:5], v[4:5], 0.5, v[8:9] op_sel_hi:[1,0,1]
	s_waitcnt vmcnt(0)
	v_pk_fma_f32 v[2:3], v[2:3], 0.5, v[14:15] op_sel_hi:[1,0,1]
	v_pk_fma_f32 v[0:1], v[0:1], 0.5, v[12:13] op_sel_hi:[1,0,1]
	global_store_dwordx4 v[16:17], v[4:7], off offset:512 sc1
	global_store_dwordx4 v[16:17], v[0:3], off offset:528 sc1
